# lrupf: LRU gemm_phase prefetches the next tile's 12 A/B loads right after the current tile's staging (hidden behind MFMA tail + epilogue)
# speedup vs baseline: 1.0108x; 1.0022x over previous
;   __host__ __device__ __forceinline__ float* G() const { return (float*)(wsl() + OFF_G); }
; __device__ __forceinline__ int obid() { int t = blockIdx.x; asm volatile("" : "+s"(t)); return t; }
; template <int EPI>
; __device__ __forceinline__ void gemm_tile(const Params& p, const EpiArgs& ea, const bf16_t* __restrict__ A, int lda,
;                                           const bf16_t* __restrict__ Bt, int K, int m0, int n0, char* smem) {
;     ...
;   const int srow = tid >> 3, sch = (tid & 7) * 8;
;   const bf16_t* ap = A + (size_t)(m0 + srow) * lda + sch;
;   const bf16_t* bp = Bt + (size_t)(n0 + srow) * K + sch;
;   const size_t a_step = (size_t)64 * lda, b_step = (size_t)64 * K;
;   uint4 ra[4], rb[2];
;   const int nk = K >> 6;
; #pragma unroll
;   for (int i = 0; i < 4; ++i) ra[i] = *(const uint4*)(ap + i * a_step);
; #pragma unroll
;   for (int i = 0; i < 2; ++i) rb[i] = *(const uint4*)(bp + i * b_step);
; template <int EPI>
; __device__ __forceinline__ void gemm_phase(const Params& p, const EpiArgs& ea, const bf16_t* A, int lda, const bf16_t* Bt, int K,
;                            int Mtiles, int Ntiles, int a_mode, int rot, char* smem) {
;   const int G = gridDim.x;
;   const int ntiles = Mtiles * Ntiles;
;   int vb = obid() - (rot % G); if (vb < 0) vb += G;
;   const int nxcd = 8;
;   const int per = G / nxcd;
;   const int x = vb % nxcd, kk = vb / nxcd;
;   for (int r = 0;; ++r) {
;     int L = (r * nxcd + x) * per + kk;
;     if (L >= ntiles) { if ((r * nxcd) * per >= ntiles) break; else continue; }
;     int band = L / (4 * Ntiles);
;     int rem = L - band * 4 * Ntiles;
;     int bm = Mtiles - band * 4; if (bm > 4) bm = 4;
;     int nt = rem / bm, mi = rem - nt * bm;
;     int mt = band * 4 + mi;
;     const bf16_t* Ap = A;
;     if (a_mode == 1) Ap = A + (nt >> 1) * 128;
;     gemm_tile<EPI>(p, ea, Ap, lda, Bt, K, mt * 256, nt * 128, smem);
.LBB0_147:
	s_andn2_b64 vcc, exec, s[2:3]
	s_cbranch_vccnz .LBB0_286
	s_load_dwordx2 s[40:41], s[0:1], 0xf0
	v_readlane_b32 s3, v255, 55
	s_mov_b32 s2, s82
	s_mov_b32 s8, 0
	s_waitcnt lgkmcnt(0)
	s_add_u32 s42, s40, 0xcd50000
	s_addc_u32 s43, s41, 0
	s_and_b32 s3, s3, 0xff
	s_lshl_b32 s3, s3, 19
	s_add_u32 s3, s40, s3
	s_addc_u32 s4, s41, 0
	s_add_u32 s44, s3, 0x5090000
	s_addc_u32 s45, s4, 0
	s_ashr_i32 s3, s2, 31
	s_and_b32 s3, s3, s80
	s_add_i32 s2, s3, s2
	s_ashr_i32 s3, s2, 31
	s_lshr_b32 s3, s3, 29
	s_add_i32 s3, s2, s3
	s_ashr_i32 s7, s3, 3
	s_and_b32 s3, s3, -8
	s_sub_i32 s2, s2, s3
	v_readlane_b32 s3, v255, 56
	s_lshl_b32 s6, s3, 10
	v_readlane_b32 s3, v254, 6
	s_mul_i32 s2, s3, s2
	s_add_i32 s7, s7, s2
	s_mov_b32 s60, s7
	s_cmpk_lt_u32 s60, 0x420
	s_cbranch_scc0 .Llru_pf_skip0
	s_lshr_b32 s61, s60, 6
	s_and_b32 s62, s60, 63
	s_cmp_lt_u32 s61, 16
	s_cselect_b32 s63, 2, 1
	s_lshr_b32 s64, s62, s63
	s_lshl_b32 s65, s64, s63
	s_sub_i32 s65, s62, s65
	s_lshl_b32 s66, s61, 2
	s_add_i32 s65, s65, s66
	s_lshl_b32 s66, s64, 6
	s_and_b32 s66, s66, 0xffffff80
	s_lshl_b32 s66, s66, 1
	s_add_u32 s66, s40, s66
	s_addc_u32 s67, s41, 0
	s_lshl_b32 s65, s65, 8
	v_ashrrev_i32_e32 v184, 3, v164
	v_add_u32_e32 v180, s65, v184
	v_ashrrev_i32_e32 v181, 31, v180
	v_lshlrev_b64 v[180:181], 11, v[180:181]
	v_lshl_add_u64 v[180:181], s[66:67], 0, v[180:181]
	v_lshlrev_b32_e32 v182, 4, v164
	v_and_b32_e32 v182, 0x70, v182
	v_mov_b32_e32 v183, 0
	v_lshl_add_u64 v[180:181], v[180:181], 0, v[182:183]
	v_lshl_add_u32 v186, s64, 7, v184
	v_ashrrev_i32_e32 v187, 31, v186
	v_lshlrev_b64 v[186:187], 8, v[186:187]
	v_lshl_add_u64 v[186:187], s[44:45], 0, v[186:187]
	v_lshl_add_u64 v[186:187], v[186:187], 0, v[182:183]
	global_load_dwordx4 v[120:123], v[180:181], off
	global_load_dwordx4 v[144:147], v[180:181], off offset:128
	global_load_dwordx4 v[136:139], v[186:187], off
	global_load_dwordx4 v[148:151], v[186:187], off offset:128
	s_mov_b64 s[62:63], 0x20000
	v_lshl_add_u64 v[190:191], v[180:181], 0, s[62:63]
	global_load_dwordx4 v[124:127], v[190:191], off
	global_load_dwordx4 v[152:155], v[190:191], off offset:128
	v_lshl_add_u64 v[190:191], v[190:191], 0, s[62:63]
	global_load_dwordx4 v[128:131], v[190:191], off
	global_load_dwordx4 v[156:159], v[190:191], off offset:128
	v_lshl_add_u64 v[190:191], v[190:191], 0, s[62:63]
	global_load_dwordx4 v[132:135], v[190:191], off
	global_load_dwordx4 v[160:163], v[190:191], off offset:128
	s_mov_b64 s[62:63], 0x4000
	v_lshl_add_u64 v[190:191], v[186:187], 0, s[62:63]
	global_load_dwordx4 v[140:143], v[190:191], off
	global_load_dwordx4 v[172:175], v[190:191], off offset:128
.Llru_pf_skip0:
	s_waitcnt vmcnt(0)
	s_branch .LBB0_150

; template <int EPI>
; __device__ __forceinline__ void gemm_tile(const Params& p, const EpiArgs& ea, const bf16_t* __restrict__ A, int lda,
;                                           const bf16_t* __restrict__ Bt, int K, int m0, int n0, char* smem) {
;     ...
;   const int srow = tid >> 3, sch = (tid & 7) * 8;
;   const bf16_t* ap = A + (size_t)(m0 + srow) * lda + sch;
;   const bf16_t* bp = Bt + (size_t)(n0 + srow) * K + sch;
;   const size_t a_step = (size_t)64 * lda, b_step = (size_t)64 * K;
;   uint4 ra[4], rb[2];
;   const int nk = K >> 6;
; #pragma unroll
;   for (int i = 0; i < 4; ++i) ra[i] = *(const uint4*)(ap + i * a_step);
; #pragma unroll
;   for (int i = 0; i < 2; ++i) rb[i] = *(const uint4*)(bp + i * b_step);
; #pragma unroll
;   for (int i = 0; i < 4; ++i) *(uint4*)(sA + (srow + i * 64) * LDT + sch) = ra[i];
; #pragma unroll
;   for (int i = 0; i < 2; ++i) *(uint4*)(sB + (srow + i * 64) * LDT + sch) = rb[i];
;   __syncthreads();
;   for (int kt = 0; kt < nk; ++kt) {
;     const int buf = kt & 1;
;     if (kt + 1 < nk) {
; #pragma unroll
;       for (int i = 0; i < 4; ++i) ra[i] = *(const uint4*)(ap + i * a_step + (kt + 1) * 64);
; #pragma unroll
;       for (int i = 0; i < 2; ++i) rb[i] = *(const uint4*)(bp + i * b_step + (kt + 1) * 64);
;     }
;     const bf16_t* cA = sA + buf * 256 * LDT + (wm * 64 + fr) * LDT + fq * 8;
;     const bf16_t* cB = sB + buf * 128 * LDT + (wn * 64 + fr) * LDT + fq * 8;
; #pragma unroll
;     for (int ks = 0; ks < 2; ++ks) {
;       bf16x8 af[4], bfg[4];
; #pragma unroll
;       for (int mi = 0; mi < 4; ++mi) af[mi] = *(const bf16x8*)(cA + mi * 16 * LDT + ks * 32);
; #pragma unroll
; template <int EPI>
; __device__ __forceinline__ void gemm_phase(const Params& p, const EpiArgs& ea, const bf16_t* A, int lda, const bf16_t* Bt, int K,
;                            int Mtiles, int Ntiles, int a_mode, int rot, char* smem) {
;     ...
;     int L = (r * nxcd + x) * per + kk;
;     if (L >= ntiles) { if ((r * nxcd) * per >= ntiles) break; else continue; }
;     int band = L / (4 * Ntiles);
;     int rem = L - band * 4 * Ntiles;
;     int bm = Mtiles - band * 4; if (bm > 4) bm = 4;
;     int nt = rem / bm, mi = rem - nt * bm;
;     int mt = band * 4 + mi;
;     const bf16_t* Ap = A;
;     if (a_mode == 1) Ap = A + (nt >> 1) * 128;
;     gemm_tile<EPI>(p, ea, Ap, lda, Bt, K, mt * 256, nt * 128, smem);
.LBB0_150:
	s_add_i32 s4, s7, s8
	s_cmpk_lt_i32 s4, 0x420
	s_mov_b64 s[2:3], -1
	s_cbranch_scc0 .LBB0_282
	s_ashr_i32 s2, s4, 31
	s_lshr_b32 s2, s2, 26
	s_add_i32 s2, s4, s2
	s_ashr_i32 s3, s2, 6
	s_lshl_b32 s5, s3, 2
	s_sub_i32 s5, 0x42, s5
	s_min_u32 s5, s5, 4
	v_cvt_f32_ubyte0_e32 v0, s5
	v_rcp_iflag_f32_e32 v0, v0
	s_andn2_b32 s2, s2, 63
	s_sub_i32 s9, s4, s2
	s_ashr_i32 s9, s9, 31
	v_mul_f32_e32 v0, 0x4f7ffffe, v0
	v_cvt_u32_f32_e32 v0, v0
	s_sub_i32 s10, 0, s5
	s_sub_i32 s2, s9, s2
	s_add_i32 s2, s4, s2
	v_readfirstlane_b32 s11, v0
	s_mul_i32 s10, s10, s11
	s_mul_hi_u32 s10, s11, s10
	s_xor_b32 s2, s2, s9
	s_add_i32 s11, s11, s10
	s_mul_hi_u32 s10, s2, s11
	s_mul_i32 s11, s10, s5
	s_sub_i32 s2, s2, s11
	s_add_i32 s11, s10, 1
	s_sub_i32 s12, s2, s5
	s_cmp_ge_u32 s2, s5
	s_cselect_b32 s10, s11, s10
	s_cselect_b32 s2, s12, s2
	s_add_i32 s11, s10, 1
	s_cmp_ge_u32 s2, s5
	s_cselect_b32 s2, s11, s10
	s_xor_b32 s2, s2, s9
	s_sub_i32 s9, s2, s9
	s_mul_i32 s2, s5, s9
	s_mul_i32 s3, s3, 60
	s_add_i32 s2, s2, s3
	s_sub_i32 s3, s4, s2
	s_lshl_b32 s2, s9, 6
	s_and_b32 s4, s2, 0xffffff80
	s_ashr_i32 s5, s4, 31
	s_lshl_b64 s[4:5], s[4:5], 1
	s_add_u32 s10, s40, s4
	v_mov_b32_e32 v65, v164
	s_addc_u32 s11, s41, s5
	s_lshl_b32 s4, s3, 8
	s_movk_i32 s5, 0x90
	v_ashrrev_i32_e32 v4, 3, v65
	v_add_u32_e32 v0, s4, v4
	v_ashrrev_i32_e32 v1, 31, v0
	v_lshlrev_b64 v[0:1], 11, v[0:1]
	v_lshlrev_b32_e32 v2, 4, v65
	v_lshl_add_u64 v[0:1], s[10:11], 0, v[0:1]
	v_and_b32_e32 v166, 0x70, v2
	v_lshl_add_u64 v[2:3], v[0:1], 0, v[166:167]
	v_lshl_add_u32 v0, s9, 7, v4
	v_mul_lo_u32 v112, v4, s5
	v_add3_u32 v113, 0, v166, v112
	s_mov_b32 s3, 0x20000
	v_ashrrev_i32_e32 v1, 31, v0
	v_lshlrev_b64 v[0:1], 8, v[0:1]
	v_lshl_add_u64 v[0:1], s[44:45], 0, v[0:1]
	v_lshl_add_u64 v[0:1], v[0:1], 0, v[166:167]
	v_add_co_u32_e32 v4, vcc, s3, v2
	s_mov_b32 s3, 0x40000
	s_nop 0
	v_addc_co_u32_e32 v5, vcc, 0, v3, vcc
	v_add_co_u32_e32 v6, vcc, s3, v2
	s_mov_b32 s3, 0x60000
	s_nop 0
	v_addc_co_u32_e32 v7, vcc, 0, v3, vcc
	v_add_co_u32_e32 v8, vcc, s3, v2
	s_movk_i32 s3, 0x4000
	s_nop 0
	v_addc_co_u32_e32 v9, vcc, 0, v3, vcc
	v_add_co_u32_e32 v10, vcc, s3, v0
	v_readlane_b32 s3, v255, 30
	s_nop 0
	v_addc_co_u32_e32 v11, vcc, 0, v1, vcc
	v_readlane_b32 s9, v255, 29
	v_bfe_u32 v66, v65, 4, 2
	v_ashrrev_i32_e32 v64, 8, v65
	v_add3_u32 v16, s9, v166, v112
	v_and_b32_e32 v67, 15, v65
	s_waitcnt vmcnt(30)
	ds_write_b128 v113, v[120:123]
	ds_write_b128 v16, v[136:139]
	ds_write_b128 v113, v[124:127] offset:9216
	ds_write_b128 v113, v[128:131] offset:18432
	ds_write_b128 v113, v[132:135] offset:27648
	ds_write_b128 v16, v[140:143] offset:9216
	v_and_b32_e32 v12, 0xcf, v65
	v_mul_u32_u24_e32 v12, 0x90, v12
	v_lshlrev_b32_e32 v13, 4, v66
	v_add3_u32 v114, 0, v12, v13
	v_lshl_or_b32 v12, v64, 6, v67
	v_mul_lo_u32 v12, v12, s5
	s_waitcnt lgkmcnt(0)
	s_barrier
	v_add3_u32 v116, s9, v12, v13
	ds_read_b128 v[12:15], v114
	ds_read_b128 v[16:19], v114 offset:2304
	ds_read_b128 v[20:23], v114 offset:4608
	ds_read_b128 v[24:27], v114 offset:6912
	ds_read_b128 v[28:31], v116
	ds_read_b128 v[32:35], v116 offset:2304
	ds_read_b128 v[36:39], v116 offset:4608
	ds_read_b128 v[40:43], v116 offset:6912
	s_waitcnt lgkmcnt(3)
	v_mfma_f32_16x16x32_bf16 v[44:47], v[12:15], v[28:31], 0
	v_or_b32_e32 v67, s2, v67
	v_lshl_add_u32 v64, v64, 5, v67
	s_mov_b32 s9, 0xbe99999a
	s_waitcnt lgkmcnt(2)
	v_mfma_f32_16x16x32_bf16 v[48:51], v[12:15], v[32:35], 0
	s_waitcnt lgkmcnt(1)
	v_mfma_f32_16x16x32_bf16 v[52:55], v[12:15], v[36:39], 0
	s_waitcnt lgkmcnt(0)
	v_mfma_f32_16x16x32_bf16 v[12:15], v[12:15], v[40:43], 0
	v_mfma_f32_16x16x32_bf16 v[56:59], v[16:19], v[28:31], 0
	v_mfma_f32_16x16x32_bf16 v[60:63], v[16:19], v[32:35], 0
	v_mfma_f32_16x16x32_bf16 v[68:71], v[16:19], v[36:39], 0
	v_mfma_f32_16x16x32_bf16 v[16:19], v[16:19], v[40:43], 0
	v_mfma_f32_16x16x32_bf16 v[72:75], v[20:23], v[28:31], 0
	v_mfma_f32_16x16x32_bf16 v[76:79], v[20:23], v[32:35], 0
	v_mfma_f32_16x16x32_bf16 v[80:83], v[20:23], v[36:39], 0
	v_mfma_f32_16x16x32_bf16 v[20:23], v[20:23], v[40:43], 0
	v_mfma_f32_16x16x32_bf16 v[28:31], v[24:27], v[28:31], 0
	v_mfma_f32_16x16x32_bf16 v[32:35], v[24:27], v[32:35], 0
	v_mfma_f32_16x16x32_bf16 v[36:39], v[24:27], v[36:39], 0
	v_mfma_f32_16x16x32_bf16 v[24:27], v[24:27], v[40:43], 0
	ds_read_b128 v[40:43], v114 offset:64
	ds_read_b128 v[84:87], v114 offset:2368
	ds_read_b128 v[88:91], v114 offset:4672
	ds_read_b128 v[92:95], v114 offset:6976
	ds_read_b128 v[96:99], v116 offset:64
	ds_read_b128 v[100:103], v116 offset:2368
	ds_read_b128 v[104:107], v116 offset:4672
	ds_read_b128 v[108:111], v116 offset:6976
	s_waitcnt lgkmcnt(3)
	v_mfma_f32_16x16x32_bf16 v[44:47], v[40:43], v[96:99], v[44:47]
	s_waitcnt lgkmcnt(2)
	v_mfma_f32_16x16x32_bf16 v[48:51], v[40:43], v[100:103], v[48:51]
	s_waitcnt lgkmcnt(1)
	v_mfma_f32_16x16x32_bf16 v[52:55], v[40:43], v[104:107], v[52:55]
	s_waitcnt lgkmcnt(0)
	v_mfma_f32_16x16x32_bf16 v[12:15], v[40:43], v[108:111], v[12:15]
	v_mfma_f32_16x16x32_bf16 v[40:43], v[84:87], v[96:99], v[56:59]
	v_mfma_f32_16x16x32_bf16 v[56:59], v[84:87], v[100:103], v[60:63]
	v_mfma_f32_16x16x32_bf16 v[60:63], v[84:87], v[104:107], v[68:71]
	v_mfma_f32_16x16x32_bf16 v[68:71], v[88:91], v[96:99], v[72:75]
	v_mfma_f32_16x16x32_bf16 v[72:75], v[88:91], v[100:103], v[76:79]
	v_mfma_f32_16x16x32_bf16 v[76:79], v[88:91], v[104:107], v[80:83]
	v_mfma_f32_16x16x32_bf16 v[16:19], v[84:87], v[108:111], v[16:19]
	v_add3_u32 v4, s3, v166, v112
	ds_write_b128 v113, v[144:147] offset:36864
	v_mfma_f32_16x16x32_bf16 v[20:23], v[88:91], v[108:111], v[20:23]
	ds_write_b128 v4, v[148:151]
	ds_write_b128 v113, v[152:155] offset:46080
	v_mfma_f32_16x16x32_bf16 v[28:31], v[92:95], v[96:99], v[28:31]
	ds_write_b128 v113, v[156:159] offset:55296
	v_mfma_f32_16x16x32_bf16 v[32:35], v[92:95], v[100:103], v[32:35]
	ds_write_b128 v113, v[160:163] offset:64512
	v_mfma_f32_16x16x32_bf16 v[36:39], v[92:95], v[104:107], v[36:39]
	ds_write_b128 v4, v[172:175] offset:9216
	v_mfma_f32_16x16x32_bf16 v[24:27], v[92:95], v[108:111], v[24:27]
	s_waitcnt lgkmcnt(0)
	s_barrier
; __device__ __forceinline__ float sigmoidf_(float x) { return __builtin_amdgcn_rcpf(1.0f + __expf(-x)); }
; #define MFMA16(a, b, c) __builtin_amdgcn_mfma_f32_16x16x32_bf16(a, b, c, 0, 0, 0)
; template <int EPI>
; __device__ __forceinline__ void gemm_tile(const Params& p, const EpiArgs& ea, const bf16_t* __restrict__ A, int lda,
;                                           const bf16_t* __restrict__ Bt, int K, int m0, int n0, char* smem) {
;     ...
;   for (int kt = 0; kt < nk; ++kt) {
;     const int buf = kt & 1;
;     if (kt + 1 < nk) {
; #pragma unroll
;       for (int i = 0; i < 4; ++i) ra[i] = *(const uint4*)(ap + i * a_step + (kt + 1) * 64);
; #pragma unroll
;       for (int i = 0; i < 2; ++i) rb[i] = *(const uint4*)(bp + i * b_step + (kt + 1) * 64);
;     }
;     const bf16_t* cA = sA + buf * 256 * LDT + (wm * 64 + fr) * LDT + fq * 8;
;     const bf16_t* cB = sB + buf * 128 * LDT + (wn * 64 + fr) * LDT + fq * 8;
; #pragma unroll
;     for (int ks = 0; ks < 2; ++ks) {
;       bf16x8 af[4], bfg[4];
; #pragma unroll
;       for (int mi = 0; mi < 4; ++mi) af[mi] = *(const bf16x8*)(cA + mi * 16 * LDT + ks * 32);
; #pragma unroll
;       for (int ni = 0; ni < 4; ++ni) bfg[ni] = *(const bf16x8*)(cB + ni * 16 * LDT + ks * 32);
; #pragma unroll
;       for (int mi = 0; mi < 4; ++mi)
; #pragma unroll
;         for (int ni = 0; ni < 4; ++ni) acc[mi][ni] = MFMA16(af[mi], bfg[ni], acc[mi][ni]);
;     }
;     if (kt + 1 < nk) {
;       bf16_t* dA = sA + (buf ^ 1) * 256 * LDT;
;       bf16_t* dB = sB + (buf ^ 1) * 128 * LDT;
; #pragma unroll
;       for (int i = 0; i < 4; ++i) *(uint4*)(dA + (srow + i * 64) * LDT + sch) = ra[i];
; #pragma unroll
;       for (int i = 0; i < 2; ++i) *(uint4*)(dB + (srow + i * 64) * LDT + sch) = rb[i];
;     }
;     __syncthreads();
;     ...
;       for (int nh = 0; nh < 2; ++nh) {
;         int ch = (n0 >> 1) + wn * 32 + nh * 16 + fr;
;         float ba = p.lru_b_a[ea.dir * 1024 + ch], bx = p.lru_b_x[ea.dir * 1024 + ch];
;         float sp8 = -8.0f * log1pf(__expf(-p.lru_lam[ea.dir * 1024 + ch]));
; #pragma unroll
;         for (int j = 0; j < 4; ++j) {
;           float r = sigmoidf_(acc[mi][nh * 2][j] + ba);
;           float ig = sigmoidf_(acc[mi][nh * 2 + 1][j] + bx);
	v_readlane_b32 s60, v255, 24
	s_add_i32 s60, s60, s8
	s_add_i32 s60, s60, s7
	s_cmpk_lt_u32 s60, 0x420
	s_cbranch_scc0 .Llru_pf_skip1
	s_lshr_b32 s61, s60, 6
	s_and_b32 s62, s60, 63
	s_cmp_lt_u32 s61, 16
	s_cselect_b32 s63, 2, 1
	s_lshr_b32 s64, s62, s63
	s_lshl_b32 s65, s64, s63
	s_sub_i32 s65, s62, s65
	s_lshl_b32 s66, s61, 2
	s_add_i32 s65, s65, s66
	s_lshl_b32 s66, s64, 6
	s_and_b32 s66, s66, 0xffffff80
	s_lshl_b32 s66, s66, 1
	s_add_u32 s66, s40, s66
	s_addc_u32 s67, s41, 0
	s_lshl_b32 s65, s65, 8
	v_ashrrev_i32_e32 v184, 3, v164
	v_add_u32_e32 v180, s65, v184
	v_ashrrev_i32_e32 v181, 31, v180
	v_lshlrev_b64 v[180:181], 11, v[180:181]
	v_lshl_add_u64 v[180:181], s[66:67], 0, v[180:181]
	v_lshlrev_b32_e32 v182, 4, v164
	v_and_b32_e32 v182, 0x70, v182
	v_mov_b32_e32 v183, 0
	v_lshl_add_u64 v[180:181], v[180:181], 0, v[182:183]
	v_lshl_add_u32 v186, s64, 7, v184
	v_ashrrev_i32_e32 v187, 31, v186
	v_lshlrev_b64 v[186:187], 8, v[186:187]
	v_lshl_add_u64 v[186:187], s[44:45], 0, v[186:187]
	v_lshl_add_u64 v[186:187], v[186:187], 0, v[182:183]
	global_load_dwordx4 v[120:123], v[180:181], off
	global_load_dwordx4 v[144:147], v[180:181], off offset:128
	global_load_dwordx4 v[136:139], v[186:187], off
	global_load_dwordx4 v[148:151], v[186:187], off offset:128
	s_mov_b64 s[62:63], 0x20000
	v_lshl_add_u64 v[190:191], v[180:181], 0, s[62:63]
	global_load_dwordx4 v[124:127], v[190:191], off
	global_load_dwordx4 v[152:155], v[190:191], off offset:128
	v_lshl_add_u64 v[190:191], v[190:191], 0, s[62:63]
	global_load_dwordx4 v[128:131], v[190:191], off
	global_load_dwordx4 v[156:159], v[190:191], off offset:128
	v_lshl_add_u64 v[190:191], v[190:191], 0, s[62:63]
	global_load_dwordx4 v[132:135], v[190:191], off
	global_load_dwordx4 v[160:163], v[190:191], off offset:128
	s_mov_b64 s[62:63], 0x4000
	v_lshl_add_u64 v[190:191], v[186:187], 0, s[62:63]
	global_load_dwordx4 v[140:143], v[190:191], off
	global_load_dwordx4 v[172:175], v[190:191], off offset:128
.Llru_pf_skip1:
	ds_read_b128 v[0:3], v114 offset:36864
	ds_read_b128 v[4:7], v114 offset:39168
	ds_read_b128 v[8:11], v114 offset:41472
	ds_read_b128 v[80:83], v114 offset:43776
	ds_read_b128 v[84:87], v116 offset:18432
	ds_read_b128 v[88:91], v116 offset:20736
	ds_read_b128 v[92:95], v116 offset:23040
	ds_read_b128 v[96:99], v116 offset:25344
	s_waitcnt lgkmcnt(3)
	v_mfma_f32_16x16x32_bf16 v[44:47], v[0:3], v[84:87], v[44:47]
	s_waitcnt lgkmcnt(2)
	v_mfma_f32_16x16x32_bf16 v[48:51], v[0:3], v[88:91], v[48:51]
	s_waitcnt lgkmcnt(1)
	v_mfma_f32_16x16x32_bf16 v[52:55], v[0:3], v[92:95], v[52:55]
	s_waitcnt lgkmcnt(0)
	v_mfma_f32_16x16x32_bf16 v[0:3], v[0:3], v[96:99], v[12:15]
	v_mfma_f32_16x16x32_bf16 v[12:15], v[4:7], v[84:87], v[40:43]
	v_mfma_f32_16x16x32_bf16 v[40:43], v[4:7], v[88:91], v[56:59]
	v_mfma_f32_16x16x32_bf16 v[100:103], v[4:7], v[92:95], v[60:63]
	v_mfma_f32_16x16x32_bf16 v[4:7], v[4:7], v[96:99], v[16:19]
	v_mfma_f32_16x16x32_bf16 v[16:19], v[8:11], v[84:87], v[68:71]
	v_mfma_f32_16x16x32_bf16 v[68:71], v[8:11], v[88:91], v[72:75]
	v_mfma_f32_16x16x32_bf16 v[72:75], v[8:11], v[92:95], v[76:79]
	v_mfma_f32_16x16x32_bf16 v[8:11], v[8:11], v[96:99], v[20:23]
	v_mfma_f32_16x16x32_bf16 v[76:79], v[80:83], v[84:87], v[28:31]
	v_mfma_f32_16x16x32_bf16 v[84:87], v[80:83], v[88:91], v[32:35]
	v_mfma_f32_16x16x32_bf16 v[88:91], v[80:83], v[92:95], v[36:39]
	v_mfma_f32_16x16x32_bf16 v[80:83], v[80:83], v[96:99], v[24:27]
	ds_read_b128 v[20:23], v114 offset:36928
	s_nop 1
	ds_read_b128 v[24:27], v114 offset:39232
	ds_read_b128 v[92:95], v114 offset:41536
	ds_read_b128 v[96:99], v114 offset:43840
	ds_read_b128 v[104:107], v116 offset:18496
	ds_read_b128 v[108:111], v116 offset:20800
	ds_read_b128 v[112:115], v116 offset:23104
	ds_read_b128 v[116:119], v116 offset:25408
	s_waitcnt lgkmcnt(0)
	s_barrier
	s_load_dwordx2 s[2:3], s[0:1], 0xc0
	s_load_dwordx4 s[12:15], s[0:1], 0xd0
	v_mfma_f32_16x16x32_bf16 v[60:63], v[20:23], v[104:107], v[44:47]
	v_mfma_f32_16x16x32_bf16 v[44:47], v[24:27], v[104:107], v[12:15]
	v_mfma_f32_16x16x32_bf16 v[40:43], v[24:27], v[108:111], v[40:43]
	v_mfma_f32_16x16x32_bf16 v[36:39], v[24:27], v[112:115], v[100:103]
	v_mfma_f32_16x16x32_bf16 v[32:35], v[24:27], v[116:119], v[4:7]
	v_mfma_f32_16x16x32_bf16 v[24:27], v[92:95], v[108:111], v[68:71]
	s_nop 2
	v_add_u32_e32 v68, s6, v64
	v_ashrrev_i32_e32 v69, 31, v68
	v_lshlrev_b64 v[68:69], 2, v[68:69]
	v_mfma_f32_16x16x32_bf16 v[56:59], v[20:23], v[108:111], v[48:51]
	v_mfma_f32_16x16x32_bf16 v[52:55], v[20:23], v[112:115], v[52:55]
	v_mfma_f32_16x16x32_bf16 v[48:51], v[20:23], v[116:119], v[0:3]
	v_mfma_f32_16x16x32_bf16 v[20:23], v[92:95], v[112:115], v[72:75]
	s_waitcnt lgkmcnt(0)
	s_nop 1
	v_lshl_add_u64 v[72:73], s[14:15], 0, v[68:69]
	global_load_dword v67, v[72:73], off
	v_lshl_add_u64 v[74:75], s[2:3], 0, v[68:69]
	v_mfma_f32_16x16x32_bf16 v[0:3], v[96:99], v[116:119], v[80:83]
	s_mov_b32 s2, 0x3f2aaaab
	s_waitcnt vmcnt(0)
	v_mul_f32_e32 v67, 0xbfb8aa3b, v67
	global_load_dword v83, v[74:75], off
	v_exp_f32_e32 v67, v67
	v_mfma_f32_16x16x32_bf16 v[12:15], v[96:99], v[104:107], v[76:79]
	v_add_f32_e32 v70, 1.0, v67
	s_nop 1
	v_lshl_add_u64 v[76:77], s[12:13], 0, v[68:69]
	v_add_f32_e32 v68, -1.0, v70
	global_load_dword v82, v[76:77], off
	v_sub_f32_e32 v69, v68, v70
	v_add_f32_e32 v69, 1.0, v69
	v_sub_f32_e32 v68, v67, v68
	v_add_f32_e32 v71, v68, v69
	v_frexp_mant_f32_e32 v68, v70
	v_cmp_gt_f32_e32 vcc, s2, v68
	v_cvt_f64_f32_e32 v[68:69], v70
	v_frexp_exp_i32_f64_e32 v68, v[68:69]
	v_mfma_f32_16x16x32_bf16 v[28:31], v[92:95], v[104:107], v[16:19]
	s_mov_b32 s2, 0x3f317218
	s_waitcnt vmcnt(1)
;   __host__ __device__ __forceinline__ bf16_t* XC() const { return (bf16_t*)(wsl() + OFF_FFN); }
; __device__ __forceinline__ float bf2f(bf16_t h) { return __uint_as_float(((uint32_t)h) << 16); }
; __device__ __forceinline__ uint32_t pack2(float a, float b) { uint32_t r; asm("v_cvt_pk_bf16_f32 %0, %1, %2" : "=v"(r) : "v"(a), "v"(b)); return r; }
; __device__ __forceinline__ float sigmoidf_(float x) { return __builtin_amdgcn_rcpf(1.0f + __expf(-x)); }
; template <int EPI>
; __device__ __forceinline__ void gemm_tile(const Params& p, const EpiArgs& ea, const bf16_t* __restrict__ A, int lda,
;                                           const bf16_t* __restrict__ Bt, int K, int m0, int n0, char* smem) {
;     ...
;       for (int nh = 0; nh < 2; ++nh) {
;         int ch = (n0 >> 1) + wn * 32 + nh * 16 + fr;
;         float ba = p.lru_b_a[ea.dir * 1024 + ch], bx = p.lru_b_x[ea.dir * 1024 + ch];
;         float sp8 = -8.0f * log1pf(__expf(-p.lru_lam[ea.dir * 1024 + ch]));
; #pragma unroll
;         for (int j = 0; j < 4; ++j) {
;           float r = sigmoidf_(acc[mi][nh * 2][j] + ba);
;           float ig = sigmoidf_(acc[mi][nh * 2 + 1][j] + bx);
;           float la = r * sp8;
;           float x2 = 2.0f * la;
;           float poly = -x2 * (1.0f + x2 * (0.5f + x2 * (0.16666667f + x2 * (0.041666668f + x2 * (0.008333334f + x2 * 0.0013888889f)))));
;           float em = (x2 < -0.3f) ? (1.0f - __expf(x2)) : poly;
;           float u = bf2f(p.XC()[(size_t)(r0 + j) * D + ch]);
;           float inp = __builtin_amdgcn_sqrtf(fmaxf(em, 0.0f)) * (ig * u);
;           ea.outu[(size_t)(r0 + j) * D + ch] = pack2(la, inp);
	v_add_f32_e32 v60, v60, v83
	v_mfma_f32_16x16x32_bf16 v[16:19], v[92:95], v[116:119], v[8:11]
	v_mul_f32_e32 v60, 0xbfb8aa3b, v60
	v_exp_f32_e32 v60, v60
	v_mfma_f32_16x16x32_bf16 v[8:11], v[96:99], v[108:111], v[84:87]
	v_add_f32_e32 v60, 1.0, v60
	v_rcp_f32_e32 v60, v60
	s_nop 0
	v_subbrev_co_u32_e32 v84, vcc, 0, v68, vcc
	v_sub_u32_e32 v68, 0, v84
	v_ldexp_f32 v69, v70, v68
	v_add_f32_e32 v70, -1.0, v69
	v_add_f32_e32 v78, 1.0, v69
	v_ldexp_f32 v68, v71, v68
	v_add_f32_e32 v71, 1.0, v70
	v_add_f32_e32 v79, -1.0, v78
	v_sub_f32_e32 v71, v69, v71
	v_sub_f32_e32 v69, v69, v79
	v_add_f32_e32 v71, v68, v71
	v_add_f32_e32 v68, v68, v69
	v_add_f32_e32 v85, v78, v68
	v_rcp_f32_e32 v87, v85
	v_sub_f32_e32 v69, v85, v78
	v_sub_f32_e32 v86, v68, v69
	v_add_f32_e32 v69, v70, v71
	v_mfma_f32_16x16x32_bf16 v[4:7], v[96:99], v[112:115], v[88:91]
	v_sub_f32_e32 v68, v69, v70
	s_nop 1
	v_mul_f32_e32 v89, v69, v87
	v_mul_f32_e32 v70, v85, v89
	v_fma_f32 v78, v89, v85, -v70
	v_fmac_f32_e32 v78, v89, v86
	v_sub_f32_e32 v88, v71, v68
	v_add_f32_e32 v68, v70, v78
	v_sub_f32_e32 v71, v69, v68
	v_pk_add_f32 v[80:81], v[68:69], v[70:71] neg_lo:[0,1] neg_hi:[0,1]
	v_mov_b32_e32 v79, v68
	v_pk_add_f32 v[68:69], v[80:81], v[78:79] neg_lo:[0,1] neg_hi:[0,1]
	s_nop 0
	v_add_f32_e32 v69, v88, v69
	v_add_f32_e32 v68, v68, v69
	v_add_f32_e32 v69, v71, v68
	v_mul_f32_e32 v88, v87, v69
	v_mul_f32_e32 v70, v85, v88
	v_fma_f32 v78, v88, v85, -v70
	v_fmac_f32_e32 v78, v88, v86
	v_sub_f32_e32 v71, v71, v69
	v_add_f32_e32 v85, v68, v71
	v_add_f32_e32 v68, v70, v78
	v_sub_f32_e32 v71, v69, v68
	v_pk_add_f32 v[80:81], v[68:69], v[70:71] neg_lo:[0,1] neg_hi:[0,1]
	v_mov_b32_e32 v79, v68
	v_pk_add_f32 v[68:69], v[80:81], v[78:79] neg_lo:[0,1] neg_hi:[0,1]
	s_nop 0
	v_add_f32_e32 v69, v85, v69
	v_add_f32_e32 v68, v68, v69
	v_add_f32_e32 v69, v89, v88
	v_add_f32_e32 v68, v71, v68
	v_sub_f32_e32 v70, v69, v89
	v_mul_f32_e32 v68, v87, v68
	v_sub_f32_e32 v70, v88, v70
	v_add_f32_e32 v70, v70, v68
	v_add_f32_e32 v78, v69, v70
	v_mul_f32_e32 v79, v78, v78
	v_fmamk_f32 v68, v79, 0x3e9b6dac, v165
	v_fmaak_f32 v171, v79, v68, 0x3f2aaada
	v_cvt_f32_i32_e32 v68, v84
	v_sub_f32_e32 v69, v78, v69
	v_sub_f32_e32 v69, v70, v69
	v_ldexp_f32 v80, v69, 1
	v_mul_f32_e32 v69, v78, v79
	v_ldexp_f32 v71, v78, 1
	v_pk_mul_f32 v[78:79], v[68:69], v[170:171]
	s_nop 0
	v_fma_f32 v70, v68, s2, -v78
	v_fmac_f32_e32 v70, 0xb102e308, v68
	v_pk_add_f32 v[68:69], v[78:79], v[70:71]
	s_mov_b32 s2, 0x7f800000
	v_sub_f32_e32 v71, v69, v71
	v_sub_f32_e32 v71, v79, v71
	v_add_f32_e32 v81, v80, v71
	v_mov_b32_e32 v80, v78
	v_pk_add_f32 v[78:79], v[68:69], v[78:79] neg_lo:[0,1] neg_hi:[0,1]
	v_pk_add_f32 v[84:85], v[68:69], v[80:81]
	v_mov_b32_e32 v71, v68
	v_mov_b32_e32 v79, v85
	v_pk_add_f32 v[86:87], v[70:71], v[78:79] neg_lo:[0,1] neg_hi:[0,1]
	v_pk_add_f32 v[70:71], v[70:71], v[78:79]
	v_mov_b32_e32 v80, v81
	v_pk_add_f32 v[78:79], v[70:71], v[68:69] op_sel:[1,0] op_sel_hi:[0,1] neg_lo:[0,1] neg_hi:[0,1]
	v_pk_add_f32 v[88:89], v[84:85], v[78:79] op_sel_hi:[1,0] neg_lo:[0,1] neg_hi:[0,1]
	v_mov_b32_e32 v84, v85
	v_mov_b32_e32 v85, v71
	v_pk_mov_b32 v[78:79], v[68:69], v[78:79] op_sel:[1,0]
	v_mov_b32_e32 v81, v68
	v_pk_add_f32 v[78:79], v[84:85], v[78:79] neg_lo:[0,1] neg_hi:[0,1]
	v_mov_b32_e32 v88, v86
	v_pk_add_f32 v[68:69], v[80:81], v[78:79] neg_lo:[0,1] neg_hi:[0,1]
	v_mov_b32_e32 v87, v71
	v_pk_add_f32 v[78:79], v[88:89], v[68:69]
	v_cmp_neq_f32_e32 vcc, s2, v67
	v_pk_add_f32 v[80:81], v[78:79], v[78:79] op_sel:[0,1] op_sel_hi:[1,0]
	s_mov_b32 s2, 0x33800000
	v_pk_add_f32 v[70:71], v[70:71], v[80:81] op_sel:[1,0] op_sel_hi:[0,1]
	v_mov_b32_e32 v79, v70
	v_pk_add_f32 v[84:85], v[78:79], v[86:87] neg_lo:[0,1] neg_hi:[0,1]
	v_mov_b32_e32 v69, v80
	v_sub_f32_e32 v71, v78, v84
	v_pk_add_f32 v[68:69], v[68:69], v[84:85] neg_lo:[0,1] neg_hi:[0,1]
	v_sub_f32_e32 v71, v86, v71
	v_add_f32_e32 v68, v68, v71
	v_add_f32_e32 v68, v68, v69
	v_add_f32_e32 v68, v70, v68
	v_cndmask_b32_e32 v68, v225, v68, vcc
	v_cmp_ngt_f32_e32 vcc, -1.0, v67
	s_nop 1
	v_cndmask_b32_e32 v68, v226, v68, vcc
	v_cmp_neq_f32_e32 vcc, -1.0, v67
	s_nop 1
	v_cndmask_b32_e32 v68, v227, v68, vcc
	v_cmp_lt_f32_e64 vcc, |v67|, s2
	s_nop 1
	v_cndmask_b32_e32 v67, v68, v67, vcc
	v_mul_f32_e32 v84, 0xc1000000, v67
	v_mul_f32_e32 v60, v60, v84
	v_add_f32_e32 v67, v60, v60
	v_cmp_ngt_f32_e32 vcc, s9, v67
	s_and_saveexec_b64 s[2:3], vcc
	s_xor_b64 s[2:3], exec, s[2:3]
	v_fmamk_f32 v68, v67, 0x3ab60b61, v169
	v_fmaak_f32 v68, v67, v68, 0x3d2aaaab
	v_fmaak_f32 v68, v67, v68, 0x3e2aaaab
	v_fma_f32 v68, v67, v68, 0.5
	v_fma_f32 v68, v67, v68, 1.0
	v_mul_f32_e64 v78, v68, -v67
	s_andn2_saveexec_b64 s[2:3], s[2:3]
	v_mul_f32_e32 v67, 0x3fb8aa3b, v67
	v_exp_f32_e32 v67, v67
	s_nop 0
	v_sub_f32_e32 v78, 1.0, v67
	s_or_b64 exec, exec, s[2:3]
	v_and_b32_e32 v65, 0xc0, v65
	v_lshlrev_b32_e32 v66, 2, v66
	v_or3_b32 v66, v66, v65, s4
	v_and_b32_e32 v179, 0xff, v66
	v_mul_u32_u24_e32 v179, 0x90, v179
	v_and_b32_e32 v188, 63, v64
	v_lshl_add_u32 v179, v188, 1, v179
	v_bfe_u32 v188, v64, 6, 1
	v_mul_u32_u24_e32 v188, 0x9000, v188
	v_add_u32_e32 v178, v179, v188
	v_ashrrev_i32_e32 v67, 31, v66
	v_ashrrev_i32_e32 v65, 31, v64
	v_lshlrev_b64 v[68:69], 10, v[66:67]
	v_lshl_add_u64 v[80:81], v[68:69], 0, v[64:65]
	v_lshl_add_u64 v[70:71], v[80:81], 1, s[40:41]
	ds_read_u16 v67, v178 offset:0
	s_waitcnt vmcnt(0)
	v_add_f32_e32 v56, v56, v82
	v_mul_f32_e32 v56, 0xbfb8aa3b, v56
	v_exp_f32_e32 v56, v56
	v_max_f32_e32 v78, v78, v78
	v_max_f32_e32 v78, 0, v78
	v_sqrt_f32_e32 v78, v78
	v_add_f32_e32 v56, 1.0, v56
	v_rcp_f32_e32 v56, v56
	s_waitcnt lgkmcnt(0)
;   __host__ __device__ __forceinline__ bf16_t* XC() const { return (bf16_t*)(wsl() + OFF_FFN); }
; __device__ __forceinline__ float bf2f(bf16_t h) { return __uint_as_float(((uint32_t)h) << 16); }
; __device__ __forceinline__ uint32_t pack2(float a, float b) { uint32_t r; asm("v_cvt_pk_bf16_f32 %0, %1, %2" : "=v"(r) : "v"(a), "v"(b)); return r; }
; __device__ __forceinline__ float sigmoidf_(float x) { return __builtin_amdgcn_rcpf(1.0f + __expf(-x)); }
; template <int EPI>
; __device__ __forceinline__ void gemm_tile(const Params& p, const EpiArgs& ea, const bf16_t* __restrict__ A, int lda,
;                                           const bf16_t* __restrict__ Bt, int K, int m0, int n0, char* smem) {
;     ...
;       for (int nh = 0; nh < 2; ++nh) {
;         int ch = (n0 >> 1) + wn * 32 + nh * 16 + fr;
;         float ba = p.lru_b_a[ea.dir * 1024 + ch], bx = p.lru_b_x[ea.dir * 1024 + ch];
;         float sp8 = -8.0f * log1pf(__expf(-p.lru_lam[ea.dir * 1024 + ch]));
; #pragma unroll
;         for (int j = 0; j < 4; ++j) {
;           float r = sigmoidf_(acc[mi][nh * 2][j] + ba);
;           float ig = sigmoidf_(acc[mi][nh * 2 + 1][j] + bx);
;           float la = r * sp8;
;           float x2 = 2.0f * la;
;           float poly = -x2 * (1.0f + x2 * (0.5f + x2 * (0.16666667f + x2 * (0.041666668f + x2 * (0.008333334f + x2 * 0.0013888889f)))));
;           float em = (x2 < -0.3f) ? (1.0f - __expf(x2)) : poly;
;           float u = bf2f(p.XC()[(size_t)(r0 + j) * D + ch]);
;           float inp = __builtin_amdgcn_sqrtf(fmaxf(em, 0.0f)) * (ig * u);
;           ea.outu[(size_t)(r0 + j) * D + ch] = pack2(la, inp);
;         }
	v_lshlrev_b32_e32 v67, 16, v67
	v_mul_f32_e32 v56, v56, v67
	v_mul_f32_e32 v56, v78, v56
	v_cvt_pk_bf16_f32 v56, v60, v56
	v_lshl_add_u64 v[78:79], v[80:81], 2, s[42:43]
	global_store_dword v[78:79], v56, off
	v_add_f32_e32 v56, v61, v83
	v_mul_f32_e32 v56, 0xbfb8aa3b, v56
	v_exp_f32_e32 v56, v56
	s_nop 0
	v_add_f32_e32 v56, 1.0, v56
	v_rcp_f32_e32 v56, v56
	s_nop 0
	v_mul_f32_e32 v67, v56, v84
	v_add_f32_e32 v56, v67, v67
	v_cmp_ngt_f32_e32 vcc, s9, v56
	s_and_saveexec_b64 s[2:3], vcc
	s_xor_b64 s[2:3], exec, s[2:3]
	v_fmamk_f32 v60, v56, 0x3ab60b61, v169
	v_fmaak_f32 v60, v56, v60, 0x3d2aaaab
	v_fmaak_f32 v60, v56, v60, 0x3e2aaaab
	v_fma_f32 v60, v56, v60, 0.5
	v_fma_f32 v60, v56, v60, 1.0
	v_mul_f32_e64 v78, v60, -v56
	s_andn2_saveexec_b64 s[2:3], s[2:3]
	v_mul_f32_e32 v56, 0x3fb8aa3b, v56
	v_exp_f32_e32 v56, v56
	s_nop 0
	v_sub_f32_e32 v78, 1.0, v56
	s_or_b64 exec, exec, s[2:3]
	v_add_f32_e32 v56, v57, v82
	v_mul_f32_e32 v56, 0xbfb8aa3b, v56
	v_exp_f32_e32 v56, v56
	v_add_f32_e32 v62, v62, v83
	v_mul_f32_e32 v62, 0xbfb8aa3b, v62
	v_exp_f32_e32 v62, v62
	v_add_f32_e32 v56, 1.0, v56
	v_rcp_f32_e32 v79, v56
	v_or_b32_e32 v56, 1, v66
	v_ashrrev_i32_e32 v57, 31, v56
	v_lshlrev_b64 v[56:57], 10, v[56:57]
	v_lshl_add_u64 v[80:81], v[56:57], 0, v[64:65]
	v_lshl_add_u64 v[60:61], v[80:81], 1, s[40:41]
	ds_read_u16 v85, v178 offset:144
	v_max_f32_e32 v78, v78, v78
	v_max_f32_e32 v78, 0, v78
	v_sqrt_f32_e32 v78, v78
	v_add_f32_e32 v62, 1.0, v62
	v_rcp_f32_e32 v62, v62
	s_waitcnt lgkmcnt(0)
	v_lshlrev_b32_e32 v85, 16, v85
	v_mul_f32_e32 v79, v79, v85
	v_mul_f32_e32 v78, v78, v79
	v_cvt_pk_bf16_f32 v67, v67, v78
	v_lshl_add_u64 v[78:79], v[80:81], 2, s[42:43]
	v_mul_f32_e32 v62, v62, v84
	global_store_dword v[78:79], v67, off
	v_add_f32_e32 v67, v62, v62
	v_cmp_ngt_f32_e32 vcc, s9, v67
	s_and_saveexec_b64 s[2:3], vcc
	s_xor_b64 s[2:3], exec, s[2:3]
	v_fmamk_f32 v78, v67, 0x3ab60b61, v169
	v_fmaak_f32 v78, v67, v78, 0x3d2aaaab
	v_fmaak_f32 v78, v67, v78, 0x3e2aaaab
	v_fma_f32 v78, v67, v78, 0.5
	v_fma_f32 v78, v67, v78, 1.0
	v_mul_f32_e64 v85, v78, -v67
	s_andn2_saveexec_b64 s[2:3], s[2:3]
	v_mul_f32_e32 v67, 0x3fb8aa3b, v67
	v_exp_f32_e32 v67, v67
	s_nop 0
	v_sub_f32_e32 v85, 1.0, v67
	s_or_b64 exec, exec, s[2:3]
	v_or_b32_e32 v78, 2, v66
	v_ashrrev_i32_e32 v79, 31, v78
	v_lshlrev_b64 v[78:79], 10, v[78:79]
	v_lshl_add_u64 v[86:87], v[78:79], 0, v[64:65]
	v_lshl_add_u64 v[80:81], v[86:87], 1, s[40:41]
	ds_read_u16 v88, v178 offset:288
	v_add_f32_e32 v63, v63, v83
	v_mul_f32_e32 v63, 0xbfb8aa3b, v63
	v_add_f32_e32 v58, v58, v82
	v_exp_f32_e32 v63, v63
	v_mul_f32_e32 v58, 0xbfb8aa3b, v58
	v_exp_f32_e32 v58, v58
	v_max_f32_e32 v67, v85, v85
	v_add_f32_e32 v63, 1.0, v63
	v_rcp_f32_e32 v63, v63
	v_add_f32_e32 v58, 1.0, v58
	v_max_f32_e32 v67, 0, v67
	v_rcp_f32_e32 v89, v58
	v_sqrt_f32_e32 v85, v67
	v_mul_f32_e32 v67, v63, v84
	v_add_f32_e32 v58, v67, v67
	v_lshl_add_u64 v[86:87], v[86:87], 2, s[42:43]
	v_cmp_ngt_f32_e32 vcc, s9, v58
	s_waitcnt lgkmcnt(0)
	v_lshlrev_b32_e32 v63, 16, v88
	v_mul_f32_e32 v63, v89, v63
	v_mul_f32_e32 v63, v85, v63
	v_cvt_pk_bf16_f32 v62, v62, v63
	global_store_dword v[86:87], v62, off
	s_and_saveexec_b64 s[2:3], vcc
	s_xor_b64 s[2:3], exec, s[2:3]
	v_fmamk_f32 v62, v58, 0x3ab60b61, v169
	v_fmaak_f32 v62, v58, v62, 0x3d2aaaab
	v_fmaak_f32 v62, v58, v62, 0x3e2aaaab
	v_fma_f32 v62, v58, v62, 0.5
	v_fma_f32 v62, v58, v62, 1.0
	v_mul_f32_e64 v85, v62, -v58
	s_andn2_saveexec_b64 s[2:3], s[2:3]
	v_mul_f32_e32 v58, 0x3fb8aa3b, v58
	v_exp_f32_e32 v58, v58
	s_nop 0
	v_sub_f32_e32 v85, 1.0, v58
	s_or_b64 exec, exec, s[2:3]
	v_add_f32_e32 v58, v59, v82
	v_mul_f32_e32 v58, 0xbfb8aa3b, v58
	v_exp_f32_e32 v58, v58
	v_max_f32_e32 v85, v85, v85
	v_max_f32_e32 v85, 0, v85
	v_sqrt_f32_e32 v85, v85
	v_add_f32_e32 v58, 1.0, v58
	v_rcp_f32_e32 v88, v58
	v_or_b32_e32 v58, 3, v66
	v_ashrrev_i32_e32 v59, 31, v58
	v_lshlrev_b64 v[58:59], 10, v[58:59]
	v_lshl_add_u64 v[86:87], v[58:59], 0, v[64:65]
	v_lshl_add_u64 v[62:63], v[86:87], 1, s[40:41]
	ds_read_u16 v89, v178 offset:432
	v_lshl_add_u64 v[86:87], v[86:87], 2, s[42:43]
	s_mov_b32 s2, 0x3f2aaaab
	s_waitcnt lgkmcnt(0)
	v_lshlrev_b32_e32 v89, 16, v89
	v_mul_f32_e32 v88, v88, v89
	v_mul_f32_e32 v85, v85, v88
	v_cvt_pk_bf16_f32 v67, v67, v85
	global_store_dword v[86:87], v67, off
	global_load_dword v74, v[74:75], off offset:64
	s_nop 0
	global_load_dword v67, v[76:77], off offset:64
	s_nop 0
	global_load_dword v72, v[72:73], off offset:64
	s_waitcnt vmcnt(2)
	v_add_f32_e32 v52, v52, v74
	v_mul_f32_e32 v52, 0xbfb8aa3b, v52
	s_waitcnt vmcnt(0)
;   __host__ __device__ __forceinline__ bf16_t* XC() const { return (bf16_t*)(wsl() + OFF_FFN); }
; __device__ __forceinline__ float bf2f(bf16_t h) { return __uint_as_float(((uint32_t)h) << 16); }
; __device__ __forceinline__ uint32_t pack2(float a, float b) { uint32_t r; asm("v_cvt_pk_bf16_f32 %0, %1, %2" : "=v"(r) : "v"(a), "v"(b)); return r; }
; __device__ __forceinline__ float sigmoidf_(float x) { return __builtin_amdgcn_rcpf(1.0f + __expf(-x)); }
; template <int EPI>
; __device__ __forceinline__ void gemm_tile(const Params& p, const EpiArgs& ea, const bf16_t* __restrict__ A, int lda,
;                                           const bf16_t* __restrict__ Bt, int K, int m0, int n0, char* smem) {
;     ...
;       for (int nh = 0; nh < 2; ++nh) {
;         int ch = (n0 >> 1) + wn * 32 + nh * 16 + fr;
;         float ba = p.lru_b_a[ea.dir * 1024 + ch], bx = p.lru_b_x[ea.dir * 1024 + ch];
;         float sp8 = -8.0f * log1pf(__expf(-p.lru_lam[ea.dir * 1024 + ch]));
; #pragma unroll
;         for (int j = 0; j < 4; ++j) {
;           float r = sigmoidf_(acc[mi][nh * 2][j] + ba);
;           float ig = sigmoidf_(acc[mi][nh * 2 + 1][j] + bx);
;           float la = r * sp8;
;           float x2 = 2.0f * la;
;           float poly = -x2 * (1.0f + x2 * (0.5f + x2 * (0.16666667f + x2 * (0.041666668f + x2 * (0.008333334f + x2 * 0.0013888889f)))));
;           float em = (x2 < -0.3f) ? (1.0f - __expf(x2)) : poly;
;           float u = bf2f(p.XC()[(size_t)(r0 + j) * D + ch]);
;           float inp = __builtin_amdgcn_sqrtf(fmaxf(em, 0.0f)) * (ig * u);
;           ea.outu[(size_t)(r0 + j) * D + ch] = pack2(la, inp);
;         }
	v_mul_f32_e32 v72, 0xbfb8aa3b, v72
	v_exp_f32_e32 v75, v72
	v_exp_f32_e32 v52, v52
	v_add_f32_e32 v76, 1.0, v75
	v_add_f32_e32 v72, -1.0, v76
	v_sub_f32_e32 v73, v72, v76
	v_add_f32_e32 v73, 1.0, v73
	v_sub_f32_e32 v72, v75, v72
	v_add_f32_e32 v77, v72, v73
	v_frexp_mant_f32_e32 v72, v76
	v_cmp_gt_f32_e32 vcc, s2, v72
	v_cvt_f64_f32_e32 v[72:73], v76
	v_frexp_exp_i32_f64_e32 v72, v[72:73]
	v_subbrev_co_u32_e32 v85, vcc, 0, v72, vcc
	v_sub_u32_e32 v72, 0, v85
	v_ldexp_f32 v73, v76, v72
	v_add_f32_e32 v76, -1.0, v73
	v_add_f32_e32 v86, 1.0, v73
	v_ldexp_f32 v72, v77, v72
	v_add_f32_e32 v77, 1.0, v76
	v_add_f32_e32 v87, -1.0, v86
	v_sub_f32_e32 v77, v73, v77
	v_sub_f32_e32 v73, v73, v87
	v_add_f32_e32 v77, v72, v77
	v_add_f32_e32 v72, v72, v73
	v_add_f32_e32 v90, v86, v72
	v_rcp_f32_e32 v92, v90
	v_sub_f32_e32 v73, v90, v86
	v_sub_f32_e32 v91, v72, v73
	v_add_f32_e32 v73, v76, v77
	v_mul_f32_e32 v94, v73, v92
	v_sub_f32_e32 v72, v73, v76
	v_mul_f32_e32 v76, v90, v94
	v_fma_f32 v86, v94, v90, -v76
	v_fmac_f32_e32 v86, v94, v91
	v_sub_f32_e32 v93, v77, v72
	v_add_f32_e32 v72, v76, v86
	v_sub_f32_e32 v77, v73, v72
	v_pk_add_f32 v[88:89], v[72:73], v[76:77] neg_lo:[0,1] neg_hi:[0,1]
	v_mov_b32_e32 v87, v72
	v_pk_add_f32 v[72:73], v[88:89], v[86:87] neg_lo:[0,1] neg_hi:[0,1]
	s_mov_b32 s2, 0x3f317218
	v_add_f32_e32 v73, v93, v73
	v_add_f32_e32 v72, v72, v73
	v_add_f32_e32 v73, v77, v72
	v_mul_f32_e32 v93, v92, v73
	v_mul_f32_e32 v76, v90, v93
	v_fma_f32 v86, v93, v90, -v76
	v_fmac_f32_e32 v86, v93, v91
	v_sub_f32_e32 v77, v77, v73
	v_add_f32_e32 v90, v72, v77
	v_add_f32_e32 v72, v76, v86
	v_sub_f32_e32 v77, v73, v72
	v_pk_add_f32 v[88:89], v[72:73], v[76:77] neg_lo:[0,1] neg_hi:[0,1]
	v_mov_b32_e32 v87, v72
	v_pk_add_f32 v[72:73], v[88:89], v[86:87] neg_lo:[0,1] neg_hi:[0,1]
	v_add_f32_e32 v52, 1.0, v52
	v_add_f32_e32 v73, v90, v73
	v_add_f32_e32 v72, v72, v73
	v_add_f32_e32 v73, v94, v93
	v_add_f32_e32 v72, v77, v72
	v_sub_f32_e32 v76, v73, v94
	v_mul_f32_e32 v72, v92, v72
	v_sub_f32_e32 v76, v93, v76
	v_add_f32_e32 v76, v76, v72
	v_add_f32_e32 v86, v73, v76
	v_mul_f32_e32 v87, v86, v86
	v_fmamk_f32 v72, v87, 0x3e9b6dac, v165
	v_fmaak_f32 v171, v87, v72, 0x3f2aaada
	v_cvt_f32_i32_e32 v72, v85
	v_sub_f32_e32 v73, v86, v73
	v_sub_f32_e32 v73, v76, v73
	v_ldexp_f32 v85, v73, 1
	v_mul_f32_e32 v73, v86, v87
	v_ldexp_f32 v77, v86, 1
	v_pk_mul_f32 v[86:87], v[72:73], v[170:171]
	v_rcp_f32_e32 v52, v52
	v_fma_f32 v76, v72, s2, -v86
	v_fmac_f32_e32 v76, 0xb102e308, v72
	v_pk_add_f32 v[72:73], v[86:87], v[76:77]
	v_mov_b32_e32 v88, v86
	v_sub_f32_e32 v77, v73, v77
	v_sub_f32_e32 v77, v87, v77
	v_add_f32_e32 v89, v85, v77
	v_pk_add_f32 v[86:87], v[72:73], v[86:87] neg_lo:[0,1] neg_hi:[0,1]
	v_pk_add_f32 v[90:91], v[72:73], v[88:89]
	v_mov_b32_e32 v77, v72
	v_mov_b32_e32 v87, v91
	v_pk_add_f32 v[92:93], v[76:77], v[86:87] neg_lo:[0,1] neg_hi:[0,1]
	v_pk_add_f32 v[76:77], v[76:77], v[86:87]
	v_mov_b32_e32 v88, v89
	v_pk_add_f32 v[86:87], v[76:77], v[72:73] op_sel:[1,0] op_sel_hi:[0,1] neg_lo:[0,1] neg_hi:[0,1]
	v_pk_add_f32 v[94:95], v[90:91], v[86:87] op_sel_hi:[1,0] neg_lo:[0,1] neg_hi:[0,1]
	v_mov_b32_e32 v90, v91
	v_mov_b32_e32 v91, v77
	v_pk_mov_b32 v[86:87], v[72:73], v[86:87] op_sel:[1,0]
	v_mov_b32_e32 v89, v72
	v_pk_add_f32 v[86:87], v[90:91], v[86:87] neg_lo:[0,1] neg_hi:[0,1]
	v_mov_b32_e32 v94, v92
	v_pk_add_f32 v[72:73], v[88:89], v[86:87] neg_lo:[0,1] neg_hi:[0,1]
	v_mov_b32_e32 v93, v77
	v_pk_add_f32 v[86:87], v[94:95], v[72:73]
	s_mov_b32 s2, 0x7f800000
	v_pk_add_f32 v[88:89], v[86:87], v[86:87] op_sel:[0,1] op_sel_hi:[1,0]
	v_cmp_neq_f32_e32 vcc, s2, v75
	v_pk_add_f32 v[76:77], v[76:77], v[88:89] op_sel:[1,0] op_sel_hi:[0,1]
	v_mov_b32_e32 v87, v76
	v_pk_add_f32 v[90:91], v[86:87], v[92:93] neg_lo:[0,1] neg_hi:[0,1]
	v_mov_b32_e32 v73, v88
	v_sub_f32_e32 v77, v86, v90
	v_pk_add_f32 v[72:73], v[72:73], v[90:91] neg_lo:[0,1] neg_hi:[0,1]
	v_sub_f32_e32 v77, v92, v77
	v_add_f32_e32 v72, v72, v77
	v_add_f32_e32 v72, v72, v73
	v_add_f32_e32 v72, v76, v72
	v_cndmask_b32_e32 v72, v225, v72, vcc
	v_cmp_ngt_f32_e32 vcc, -1.0, v75
	s_mov_b32 s2, 0x33800000
	s_nop 0
	v_cndmask_b32_e32 v72, v226, v72, vcc
	v_cmp_neq_f32_e32 vcc, -1.0, v75
	s_nop 1
	v_cndmask_b32_e32 v72, v227, v72, vcc
	v_cmp_lt_f32_e64 vcc, |v75|, s2
	s_nop 1
	v_cndmask_b32_e32 v72, v72, v75, vcc
	v_mul_f32_e32 v72, 0xc1000000, v72
	v_mul_f32_e32 v73, v52, v72
	v_add_f32_e32 v52, v73, v73
	v_cmp_ngt_f32_e32 vcc, s9, v52
	s_and_saveexec_b64 s[2:3], vcc
	s_xor_b64 s[2:3], exec, s[2:3]
	v_fmamk_f32 v75, v52, 0x3ab60b61, v169
	v_fmaak_f32 v75, v52, v75, 0x3d2aaaab
	v_fmaak_f32 v75, v52, v75, 0x3e2aaaab
	v_fma_f32 v75, v52, v75, 0.5
	v_fma_f32 v75, v52, v75, 1.0
	v_mul_f32_e64 v75, v75, -v52
	s_andn2_saveexec_b64 s[2:3], s[2:3]
	v_mul_f32_e32 v52, 0x3fb8aa3b, v52
	v_exp_f32_e32 v52, v52
	s_nop 0
	v_sub_f32_e32 v75, 1.0, v52
	s_or_b64 exec, exec, s[2:3]
	ds_read_u16 v76, v178 offset:32
	v_add_f32_e32 v48, v48, v67
	v_add_f32_e32 v71, v53, v74
	v_mul_f32_e32 v48, 0xbfb8aa3b, v48
	v_mul_f32_e32 v71, 0xbfb8aa3b, v71
	v_exp_f32_e32 v71, v71
	v_exp_f32_e32 v48, v48
	v_or_b32_e32 v52, 16, v64
	v_max_f32_e32 v70, v75, v75
	v_ashrrev_i32_e32 v53, 31, v52
	v_max_f32_e32 v70, 0, v70
	v_lshl_add_u64 v[68:69], v[68:69], 0, v[52:53]
	v_sqrt_f32_e32 v75, v70
	v_add_f32_e32 v70, 1.0, v71
	v_add_f32_e32 v48, 1.0, v48
	v_rcp_f32_e32 v77, v70
	v_lshl_add_u64 v[70:71], v[68:69], 2, s[42:43]
	v_rcp_f32_e32 v68, v48
	v_mul_f32_e32 v48, v77, v72
	v_add_f32_e32 v69, v48, v48
	v_cmp_ngt_f32_e32 vcc, s9, v69
	s_waitcnt lgkmcnt(0)
;   __host__ __device__ __forceinline__ bf16_t* XC() const { return (bf16_t*)(wsl() + OFF_FFN); }
; __device__ __forceinline__ float bf2f(bf16_t h) { return __uint_as_float(((uint32_t)h) << 16); }
; __device__ __forceinline__ uint32_t pack2(float a, float b) { uint32_t r; asm("v_cvt_pk_bf16_f32 %0, %1, %2" : "=v"(r) : "v"(a), "v"(b)); return r; }
; __device__ __forceinline__ float sigmoidf_(float x) { return __builtin_amdgcn_rcpf(1.0f + __expf(-x)); }
; template <int EPI>
; __device__ __forceinline__ void gemm_tile(const Params& p, const EpiArgs& ea, const bf16_t* __restrict__ A, int lda,
;                                           const bf16_t* __restrict__ Bt, int K, int m0, int n0, char* smem) {
;     ...
;       for (int nh = 0; nh < 2; ++nh) {
;         int ch = (n0 >> 1) + wn * 32 + nh * 16 + fr;
;         float ba = p.lru_b_a[ea.dir * 1024 + ch], bx = p.lru_b_x[ea.dir * 1024 + ch];
;         float sp8 = -8.0f * log1pf(__expf(-p.lru_lam[ea.dir * 1024 + ch]));
; #pragma unroll
;         for (int j = 0; j < 4; ++j) {
;           float r = sigmoidf_(acc[mi][nh * 2][j] + ba);
;           float ig = sigmoidf_(acc[mi][nh * 2 + 1][j] + bx);
;           float la = r * sp8;
;           float x2 = 2.0f * la;
;           float poly = -x2 * (1.0f + x2 * (0.5f + x2 * (0.16666667f + x2 * (0.041666668f + x2 * (0.008333334f + x2 * 0.0013888889f)))));
;           float em = (x2 < -0.3f) ? (1.0f - __expf(x2)) : poly;
;           float u = bf2f(p.XC()[(size_t)(r0 + j) * D + ch]);
;           float inp = __builtin_amdgcn_sqrtf(fmaxf(em, 0.0f)) * (ig * u);
;           ea.outu[(size_t)(r0 + j) * D + ch] = pack2(la, inp);
;         }
	v_lshlrev_b32_e32 v76, 16, v76
	v_mul_f32_e32 v68, v68, v76
	v_mul_f32_e32 v68, v75, v68
	v_cvt_pk_bf16_f32 v68, v73, v68
	global_store_dword v[70:71], v68, off
	s_and_saveexec_b64 s[2:3], vcc
	s_xor_b64 s[2:3], exec, s[2:3]
	v_fmamk_f32 v68, v69, 0x3ab60b61, v169
	v_fmaak_f32 v68, v69, v68, 0x3d2aaaab
	v_fmaak_f32 v68, v69, v68, 0x3e2aaaab
	v_fma_f32 v68, v69, v68, 0.5
	v_fma_f32 v68, v69, v68, 1.0
	v_mul_f32_e64 v68, v68, -v69
	s_andn2_saveexec_b64 s[2:3], s[2:3]
	v_mul_f32_e32 v68, 0x3fb8aa3b, v69
	v_exp_f32_e32 v68, v68
	s_nop 0
	v_sub_f32_e32 v68, 1.0, v68
	s_or_b64 exec, exec, s[2:3]
	ds_read_u16 v60, v178 offset:176
	v_add_f32_e32 v54, v54, v74
	v_add_f32_e32 v49, v49, v67
	v_mul_f32_e32 v54, 0xbfb8aa3b, v54
	v_mul_f32_e32 v49, 0xbfb8aa3b, v49
	v_exp_f32_e32 v54, v54
	v_exp_f32_e32 v49, v49
	v_max_f32_e32 v61, v68, v68
	v_max_f32_e32 v61, 0, v61
	v_add_f32_e32 v54, 1.0, v54
	v_rcp_f32_e32 v54, v54
	v_add_f32_e32 v49, 1.0, v49
	v_rcp_f32_e32 v68, v49
	v_sqrt_f32_e32 v61, v61
	v_mul_f32_e32 v49, v54, v72
	v_lshl_add_u64 v[56:57], v[56:57], 0, v[52:53]
	v_add_f32_e32 v54, v49, v49
	v_lshl_add_u64 v[56:57], v[56:57], 2, s[42:43]
	v_cmp_ngt_f32_e32 vcc, s9, v54
	s_waitcnt lgkmcnt(0)
	v_lshlrev_b32_e32 v60, 16, v60
	v_mul_f32_e32 v60, v68, v60
	v_mul_f32_e32 v60, v61, v60
	v_cvt_pk_bf16_f32 v48, v48, v60
	global_store_dword v[56:57], v48, off
	s_and_saveexec_b64 s[2:3], vcc
	s_xor_b64 s[2:3], exec, s[2:3]
	v_fmamk_f32 v48, v54, 0x3ab60b61, v169
	v_fmaak_f32 v48, v54, v48, 0x3d2aaaab
	v_fmaak_f32 v48, v54, v48, 0x3e2aaaab
	v_fma_f32 v48, v54, v48, 0.5
	v_fma_f32 v48, v54, v48, 1.0
	v_mul_f32_e64 v48, v48, -v54
	s_andn2_saveexec_b64 s[2:3], s[2:3]
	v_mul_f32_e32 v48, 0x3fb8aa3b, v54
	v_exp_f32_e32 v48, v48
	s_nop 0
	v_sub_f32_e32 v48, 1.0, v48
	s_or_b64 exec, exec, s[2:3]
	ds_read_u16 v60, v178 offset:320
	v_add_f32_e32 v54, v55, v74
	v_add_f32_e32 v50, v50, v67
	v_mul_f32_e32 v54, 0xbfb8aa3b, v54
	v_mul_f32_e32 v50, 0xbfb8aa3b, v50
	v_exp_f32_e32 v61, v54
	v_exp_f32_e32 v50, v50
	v_lshl_add_u64 v[56:57], v[78:79], 0, v[52:53]
	v_max_f32_e32 v48, v48, v48
	v_max_f32_e32 v48, 0, v48
	v_lshl_add_u64 v[54:55], v[56:57], 2, s[42:43]
	v_add_f32_e32 v56, 1.0, v61
	v_rcp_f32_e32 v56, v56
	v_sqrt_f32_e32 v57, v48
	v_add_f32_e32 v48, 1.0, v50
	v_rcp_f32_e32 v61, v48
	v_mul_f32_e32 v48, v56, v72
	v_add_f32_e32 v50, v48, v48
	v_cmp_ngt_f32_e32 vcc, s9, v50
	s_waitcnt lgkmcnt(0)
	v_lshlrev_b32_e32 v56, 16, v60
	v_mul_f32_e32 v56, v61, v56
	v_mul_f32_e32 v56, v57, v56
	v_cvt_pk_bf16_f32 v49, v49, v56
	global_store_dword v[54:55], v49, off
	s_and_saveexec_b64 s[2:3], vcc
	s_xor_b64 s[2:3], exec, s[2:3]
	v_fmamk_f32 v49, v50, 0x3ab60b61, v169
	v_fmaak_f32 v49, v50, v49, 0x3d2aaaab
	v_fmaak_f32 v49, v50, v49, 0x3e2aaaab
	v_fma_f32 v49, v50, v49, 0.5
	v_fma_f32 v49, v50, v49, 1.0
	v_mul_f32_e64 v49, v49, -v50
	s_andn2_saveexec_b64 s[2:3], s[2:3]
	v_mul_f32_e32 v49, 0x3fb8aa3b, v50
	v_exp_f32_e32 v49, v49
	s_nop 0
	v_sub_f32_e32 v49, 1.0, v49
	s_or_b64 exec, exec, s[2:3]
	ds_read_u16 v54, v178 offset:464
	v_add_f32_e32 v44, v44, v83
	v_add_f32_e32 v55, v51, v67
	v_mul_f32_e32 v44, 0xbfb8aa3b, v44
	v_mul_f32_e32 v55, 0xbfb8aa3b, v55
	v_exp_f32_e32 v44, v44
	v_exp_f32_e32 v55, v55
	v_max_f32_e32 v49, v49, v49
	v_max_f32_e32 v49, 0, v49
	v_add_f32_e32 v44, 1.0, v44
	v_rcp_f32_e32 v44, v44
	v_sqrt_f32_e32 v56, v49
	v_add_f32_e32 v49, 1.0, v55
	v_rcp_f32_e32 v55, v49
	v_mul_f32_e32 v44, v44, v84
	v_lshl_add_u64 v[50:51], v[58:59], 0, v[52:53]
	v_add_f32_e32 v49, v44, v44
	v_lshl_add_u64 v[50:51], v[50:51], 2, s[42:43]
	v_cmp_ngt_f32_e32 vcc, s9, v49
	s_waitcnt lgkmcnt(0)
	v_lshlrev_b32_e32 v54, 16, v54
	v_mul_f32_e32 v54, v55, v54
	v_mul_f32_e32 v54, v56, v54
	v_cvt_pk_bf16_f32 v48, v48, v54
	global_store_dword v[50:51], v48, off
	s_and_saveexec_b64 s[2:3], vcc
	s_xor_b64 s[2:3], exec, s[2:3]
	v_fmamk_f32 v48, v49, 0x3ab60b61, v169
	v_fmaak_f32 v48, v49, v48, 0x3d2aaaab
	v_fmaak_f32 v48, v49, v48, 0x3e2aaaab
	v_fma_f32 v48, v49, v48, 0.5
	v_fma_f32 v48, v49, v48, 1.0
	v_mul_f32_e64 v54, v48, -v49
	s_andn2_saveexec_b64 s[2:3], s[2:3]
	v_mul_f32_e32 v48, 0x3fb8aa3b, v49
	v_exp_f32_e32 v48, v48
	s_nop 0
	v_sub_f32_e32 v54, 1.0, v48
	s_or_b64 exec, exec, s[2:3]
	v_or_b32_e32 v48, 16, v66
	v_ashrrev_i32_e32 v49, 31, v48
	v_lshlrev_b64 v[48:49], 10, v[48:49]
	v_lshl_add_u64 v[56:57], v[48:49], 0, v[64:65]
	v_lshl_add_u64 v[50:51], v[56:57], 1, s[40:41]
	ds_read_u16 v55, v178 offset:2304
	v_add_f32_e32 v40, v40, v82
	v_mul_f32_e32 v40, 0xbfb8aa3b, v40
	v_exp_f32_e32 v40, v40
	v_max_f32_e32 v54, v54, v54
	v_max_f32_e32 v54, 0, v54
	v_sqrt_f32_e32 v54, v54
	v_add_f32_e32 v40, 1.0, v40
	v_rcp_f32_e32 v40, v40
	s_waitcnt lgkmcnt(0)
	v_lshlrev_b32_e32 v55, 16, v55
	v_mul_f32_e32 v40, v40, v55
	v_mul_f32_e32 v40, v54, v40
	v_cvt_pk_bf16_f32 v40, v44, v40
	v_lshl_add_u64 v[54:55], v[56:57], 2, s[42:43]
	global_store_dword v[54:55], v40, off
	v_add_f32_e32 v40, v45, v83
	v_mul_f32_e32 v40, 0xbfb8aa3b, v40
	v_exp_f32_e32 v40, v40
	s_nop 0
	v_add_f32_e32 v40, 1.0, v40
	v_rcp_f32_e32 v40, v40
	s_nop 0
	v_mul_f32_e32 v54, v40, v84
	v_add_f32_e32 v40, v54, v54
	v_cmp_ngt_f32_e32 vcc, s9, v40
	s_and_saveexec_b64 s[2:3], vcc
	s_xor_b64 s[2:3], exec, s[2:3]
	v_fmamk_f32 v44, v40, 0x3ab60b61, v169
	v_fmaak_f32 v44, v40, v44, 0x3d2aaaab
	v_fmaak_f32 v44, v40, v44, 0x3e2aaaab
	v_fma_f32 v44, v40, v44, 0.5
	v_fma_f32 v44, v40, v44, 1.0
	v_mul_f32_e64 v55, v44, -v40
	s_andn2_saveexec_b64 s[2:3], s[2:3]
	v_mul_f32_e32 v40, 0x3fb8aa3b, v40
	v_exp_f32_e32 v40, v40
	s_nop 0
	v_sub_f32_e32 v55, 1.0, v40
	s_or_b64 exec, exec, s[2:3]
	v_add_f32_e32 v40, v41, v82
	v_mul_f32_e32 v40, 0xbfb8aa3b, v40
	v_exp_f32_e32 v40, v40
	v_add_f32_e32 v46, v46, v83
	v_mul_f32_e32 v46, 0xbfb8aa3b, v46
	v_exp_f32_e32 v46, v46
	v_add_f32_e32 v40, 1.0, v40
	v_rcp_f32_e32 v58, v40
	v_or_b32_e32 v40, 17, v66
	v_ashrrev_i32_e32 v41, 31, v40
	v_lshlrev_b64 v[40:41], 10, v[40:41]
	v_lshl_add_u64 v[56:57], v[40:41], 0, v[64:65]
	v_lshl_add_u64 v[44:45], v[56:57], 1, s[40:41]
	ds_read_u16 v59, v178 offset:2448
	v_max_f32_e32 v55, v55, v55
	v_max_f32_e32 v55, 0, v55
	v_sqrt_f32_e32 v55, v55
	v_add_f32_e32 v46, 1.0, v46
	v_rcp_f32_e32 v46, v46
	s_waitcnt lgkmcnt(0)
;   __host__ __device__ __forceinline__ bf16_t* XC() const { return (bf16_t*)(wsl() + OFF_FFN); }
; __device__ __forceinline__ float bf2f(bf16_t h) { return __uint_as_float(((uint32_t)h) << 16); }
; __device__ __forceinline__ uint32_t pack2(float a, float b) { uint32_t r; asm("v_cvt_pk_bf16_f32 %0, %1, %2" : "=v"(r) : "v"(a), "v"(b)); return r; }
; __device__ __forceinline__ float sigmoidf_(float x) { return __builtin_amdgcn_rcpf(1.0f + __expf(-x)); }
; template <int EPI>
; __device__ __forceinline__ void gemm_tile(const Params& p, const EpiArgs& ea, const bf16_t* __restrict__ A, int lda,
;                                           const bf16_t* __restrict__ Bt, int K, int m0, int n0, char* smem) {
;     ...
;       for (int nh = 0; nh < 2; ++nh) {
;         int ch = (n0 >> 1) + wn * 32 + nh * 16 + fr;
;         float ba = p.lru_b_a[ea.dir * 1024 + ch], bx = p.lru_b_x[ea.dir * 1024 + ch];
;         float sp8 = -8.0f * log1pf(__expf(-p.lru_lam[ea.dir * 1024 + ch]));
; #pragma unroll
;         for (int j = 0; j < 4; ++j) {
;           float r = sigmoidf_(acc[mi][nh * 2][j] + ba);
;           float ig = sigmoidf_(acc[mi][nh * 2 + 1][j] + bx);
;           float la = r * sp8;
;           float x2 = 2.0f * la;
;           float poly = -x2 * (1.0f + x2 * (0.5f + x2 * (0.16666667f + x2 * (0.041666668f + x2 * (0.008333334f + x2 * 0.0013888889f)))));
;           float em = (x2 < -0.3f) ? (1.0f - __expf(x2)) : poly;
;           float u = bf2f(p.XC()[(size_t)(r0 + j) * D + ch]);
;           float inp = __builtin_amdgcn_sqrtf(fmaxf(em, 0.0f)) * (ig * u);
;           ea.outu[(size_t)(r0 + j) * D + ch] = pack2(la, inp);
;         }
	v_lshlrev_b32_e32 v59, 16, v59
	v_mul_f32_e32 v58, v58, v59
	v_mul_f32_e32 v55, v55, v58
	v_cvt_pk_bf16_f32 v58, v54, v55
	v_lshl_add_u64 v[54:55], v[56:57], 2, s[42:43]
	v_mul_f32_e32 v46, v46, v84
	global_store_dword v[54:55], v58, off
	v_add_f32_e32 v54, v46, v46
	v_cmp_ngt_f32_e32 vcc, s9, v54
	s_and_saveexec_b64 s[2:3], vcc
	s_xor_b64 s[2:3], exec, s[2:3]
	v_fmamk_f32 v55, v54, 0x3ab60b61, v169
	v_fmaak_f32 v55, v54, v55, 0x3d2aaaab
	v_fmaak_f32 v55, v54, v55, 0x3e2aaaab
	v_fma_f32 v55, v54, v55, 0.5
	v_fma_f32 v55, v54, v55, 1.0
	v_mul_f32_e64 v58, v55, -v54
	s_andn2_saveexec_b64 s[2:3], s[2:3]
	v_mul_f32_e32 v54, 0x3fb8aa3b, v54
	v_exp_f32_e32 v54, v54
	s_nop 0
	v_sub_f32_e32 v58, 1.0, v54
	s_or_b64 exec, exec, s[2:3]
	v_or_b32_e32 v54, 18, v66
	v_ashrrev_i32_e32 v55, 31, v54
	v_lshlrev_b64 v[54:55], 10, v[54:55]
	v_lshl_add_u64 v[60:61], v[54:55], 0, v[64:65]
	v_lshl_add_u64 v[56:57], v[60:61], 1, s[40:41]
	ds_read_u16 v59, v178 offset:2592
	v_add_f32_e32 v47, v47, v83
	v_mul_f32_e32 v47, 0xbfb8aa3b, v47
	v_add_f32_e32 v42, v42, v82
	v_exp_f32_e32 v47, v47
	v_mul_f32_e32 v42, 0xbfb8aa3b, v42
	v_exp_f32_e32 v42, v42
	v_max_f32_e32 v58, v58, v58
	v_add_f32_e32 v47, 1.0, v47
	v_rcp_f32_e32 v47, v47
	v_add_f32_e32 v42, 1.0, v42
	v_max_f32_e32 v58, 0, v58
	v_rcp_f32_e32 v63, v42
	v_sqrt_f32_e32 v62, v58
	v_mul_f32_e32 v58, v47, v84
	v_add_f32_e32 v42, v58, v58
	v_lshl_add_u64 v[60:61], v[60:61], 2, s[42:43]
	v_cmp_ngt_f32_e32 vcc, s9, v42
	s_waitcnt lgkmcnt(0)
	v_lshlrev_b32_e32 v47, 16, v59
	v_mul_f32_e32 v47, v63, v47
	v_mul_f32_e32 v47, v62, v47
	v_cvt_pk_bf16_f32 v46, v46, v47
	global_store_dword v[60:61], v46, off
	s_and_saveexec_b64 s[2:3], vcc
	s_xor_b64 s[2:3], exec, s[2:3]
	v_fmamk_f32 v46, v42, 0x3ab60b61, v169
	v_fmaak_f32 v46, v42, v46, 0x3d2aaaab
	v_fmaak_f32 v46, v42, v46, 0x3e2aaaab
	v_fma_f32 v46, v42, v46, 0.5
	v_fma_f32 v46, v42, v46, 1.0
	v_mul_f32_e64 v59, v46, -v42
	s_andn2_saveexec_b64 s[2:3], s[2:3]
	v_mul_f32_e32 v42, 0x3fb8aa3b, v42
	v_exp_f32_e32 v42, v42
	s_nop 0
	v_sub_f32_e32 v59, 1.0, v42
	s_or_b64 exec, exec, s[2:3]
	v_add_f32_e32 v42, v43, v82
	v_mul_f32_e32 v42, 0xbfb8aa3b, v42
	v_exp_f32_e32 v42, v42
	v_add_f32_e32 v36, v36, v74
	v_mul_f32_e32 v36, 0xbfb8aa3b, v36
	v_exp_f32_e32 v36, v36
	v_add_f32_e32 v42, 1.0, v42
	v_rcp_f32_e32 v62, v42
	v_or_b32_e32 v42, 19, v66
	v_ashrrev_i32_e32 v43, 31, v42
	v_lshlrev_b64 v[42:43], 10, v[42:43]
	v_lshl_add_u64 v[60:61], v[42:43], 0, v[64:65]
	v_lshl_add_u64 v[46:47], v[60:61], 1, s[40:41]
	ds_read_u16 v63, v178 offset:2736
	v_max_f32_e32 v59, v59, v59
	v_max_f32_e32 v59, 0, v59
	v_sqrt_f32_e32 v59, v59
	v_add_f32_e32 v36, 1.0, v36
	v_rcp_f32_e32 v36, v36
	s_waitcnt lgkmcnt(0)
	v_lshlrev_b32_e32 v63, 16, v63
	v_mul_f32_e32 v62, v62, v63
	v_mul_f32_e32 v59, v59, v62
	v_cvt_pk_bf16_f32 v62, v58, v59
	v_lshl_add_u64 v[58:59], v[60:61], 2, s[42:43]
	v_mul_f32_e32 v36, v36, v72
	global_store_dword v[58:59], v62, off
	v_add_f32_e32 v58, v36, v36
	v_cmp_ngt_f32_e32 vcc, s9, v58
	s_and_saveexec_b64 s[2:3], vcc
	s_xor_b64 s[2:3], exec, s[2:3]
	v_fmamk_f32 v59, v58, 0x3ab60b61, v169
	v_fmaak_f32 v59, v58, v59, 0x3d2aaaab
	v_fmaak_f32 v59, v58, v59, 0x3e2aaaab
	v_fma_f32 v59, v58, v59, 0.5
	v_fma_f32 v59, v58, v59, 1.0
	v_mul_f32_e64 v59, v59, -v58
	s_andn2_saveexec_b64 s[2:3], s[2:3]
	v_mul_f32_e32 v58, 0x3fb8aa3b, v58
	v_exp_f32_e32 v58, v58
	s_nop 0
	v_sub_f32_e32 v59, 1.0, v58
	s_or_b64 exec, exec, s[2:3]
	ds_read_u16 v50, v178 offset:2336
	v_add_f32_e32 v37, v37, v74
	v_add_f32_e32 v32, v32, v67
	v_mul_f32_e32 v37, 0xbfb8aa3b, v37
	v_mul_f32_e32 v32, 0xbfb8aa3b, v32
	v_exp_f32_e32 v37, v37
	v_exp_f32_e32 v32, v32
	v_max_f32_e32 v51, v59, v59
	v_max_f32_e32 v51, 0, v51
	v_add_f32_e32 v37, 1.0, v37
	v_rcp_f32_e32 v37, v37
	v_add_f32_e32 v32, 1.0, v32
	v_rcp_f32_e32 v58, v32
	v_sqrt_f32_e32 v51, v51
	v_mul_f32_e32 v32, v37, v72
	v_lshl_add_u64 v[48:49], v[48:49], 0, v[52:53]
	v_add_f32_e32 v37, v32, v32
	v_lshl_add_u64 v[48:49], v[48:49], 2, s[42:43]
	v_cmp_ngt_f32_e32 vcc, s9, v37
	s_waitcnt lgkmcnt(0)
	v_lshlrev_b32_e32 v50, 16, v50
	v_mul_f32_e32 v50, v58, v50
	v_mul_f32_e32 v50, v51, v50
	v_cvt_pk_bf16_f32 v36, v36, v50
	global_store_dword v[48:49], v36, off
	s_and_saveexec_b64 s[2:3], vcc
	s_xor_b64 s[2:3], exec, s[2:3]
	v_fmamk_f32 v36, v37, 0x3ab60b61, v169
	v_fmaak_f32 v36, v37, v36, 0x3d2aaaab
	v_fmaak_f32 v36, v37, v36, 0x3e2aaaab
	v_fma_f32 v36, v37, v36, 0.5
	v_fma_f32 v36, v37, v36, 1.0
	v_mul_f32_e64 v36, v36, -v37
	s_andn2_saveexec_b64 s[2:3], s[2:3]
	v_mul_f32_e32 v36, 0x3fb8aa3b, v37
	v_exp_f32_e32 v36, v36
	s_nop 0
	v_sub_f32_e32 v36, 1.0, v36
	s_or_b64 exec, exec, s[2:3]
	ds_read_u16 v37, v178 offset:2480
	v_add_f32_e32 v38, v38, v74
	v_add_f32_e32 v33, v33, v67
	v_mul_f32_e32 v38, 0xbfb8aa3b, v38
	v_mul_f32_e32 v33, 0xbfb8aa3b, v33
	v_exp_f32_e32 v38, v38
	v_exp_f32_e32 v33, v33
	v_max_f32_e32 v36, v36, v36
	v_max_f32_e32 v36, 0, v36
	v_add_f32_e32 v38, 1.0, v38
	v_rcp_f32_e32 v38, v38
	v_add_f32_e32 v33, 1.0, v33
	v_rcp_f32_e32 v45, v33
	v_sqrt_f32_e32 v44, v36
	v_mul_f32_e32 v33, v38, v72
	v_lshl_add_u64 v[40:41], v[40:41], 0, v[52:53]
	v_add_f32_e32 v36, v33, v33
	v_lshl_add_u64 v[40:41], v[40:41], 2, s[42:43]
	v_cmp_ngt_f32_e32 vcc, s9, v36
	s_waitcnt lgkmcnt(0)
;   __host__ __device__ __forceinline__ bf16_t* XC() const { return (bf16_t*)(wsl() + OFF_FFN); }
; __device__ __forceinline__ float bf2f(bf16_t h) { return __uint_as_float(((uint32_t)h) << 16); }
; __device__ __forceinline__ uint32_t pack2(float a, float b) { uint32_t r; asm("v_cvt_pk_bf16_f32 %0, %1, %2" : "=v"(r) : "v"(a), "v"(b)); return r; }
; __device__ __forceinline__ float sigmoidf_(float x) { return __builtin_amdgcn_rcpf(1.0f + __expf(-x)); }
; template <int EPI>
; __device__ __forceinline__ void gemm_tile(const Params& p, const EpiArgs& ea, const bf16_t* __restrict__ A, int lda,
;                                           const bf16_t* __restrict__ Bt, int K, int m0, int n0, char* smem) {
;     ...
;       for (int nh = 0; nh < 2; ++nh) {
;         int ch = (n0 >> 1) + wn * 32 + nh * 16 + fr;
;         float ba = p.lru_b_a[ea.dir * 1024 + ch], bx = p.lru_b_x[ea.dir * 1024 + ch];
;         float sp8 = -8.0f * log1pf(__expf(-p.lru_lam[ea.dir * 1024 + ch]));
; #pragma unroll
;         for (int j = 0; j < 4; ++j) {
;           float r = sigmoidf_(acc[mi][nh * 2][j] + ba);
;           float ig = sigmoidf_(acc[mi][nh * 2 + 1][j] + bx);
;           float la = r * sp8;
;           float x2 = 2.0f * la;
;           float poly = -x2 * (1.0f + x2 * (0.5f + x2 * (0.16666667f + x2 * (0.041666668f + x2 * (0.008333334f + x2 * 0.0013888889f)))));
;           float em = (x2 < -0.3f) ? (1.0f - __expf(x2)) : poly;
;           float u = bf2f(p.XC()[(size_t)(r0 + j) * D + ch]);
;           float inp = __builtin_amdgcn_sqrtf(fmaxf(em, 0.0f)) * (ig * u);
;           ea.outu[(size_t)(r0 + j) * D + ch] = pack2(la, inp);
;         }
	v_lshlrev_b32_e32 v37, 16, v37
	v_mul_f32_e32 v37, v45, v37
	v_mul_f32_e32 v37, v44, v37
	v_cvt_pk_bf16_f32 v32, v32, v37
	global_store_dword v[40:41], v32, off
	s_and_saveexec_b64 s[2:3], vcc
	s_xor_b64 s[2:3], exec, s[2:3]
	v_fmamk_f32 v32, v36, 0x3ab60b61, v169
	v_fmaak_f32 v32, v36, v32, 0x3d2aaaab
	v_fmaak_f32 v32, v36, v32, 0x3e2aaaab
	v_fma_f32 v32, v36, v32, 0.5
	v_fma_f32 v32, v36, v32, 1.0
	v_mul_f32_e64 v32, v32, -v36
	s_andn2_saveexec_b64 s[2:3], s[2:3]
	v_mul_f32_e32 v32, 0x3fb8aa3b, v36
	v_exp_f32_e32 v32, v32
	s_nop 0
	v_sub_f32_e32 v32, 1.0, v32
	s_or_b64 exec, exec, s[2:3]
	ds_read_u16 v38, v178 offset:2624
	v_add_f32_e32 v39, v39, v74
	v_add_f32_e32 v34, v34, v67
	v_mul_f32_e32 v39, 0xbfb8aa3b, v39
	v_mul_f32_e32 v34, 0xbfb8aa3b, v34
	v_exp_f32_e32 v39, v39
	v_exp_f32_e32 v34, v34
	v_max_f32_e32 v32, v32, v32
	v_max_f32_e32 v32, 0, v32
	v_add_f32_e32 v39, 1.0, v39
	v_rcp_f32_e32 v39, v39
	v_sqrt_f32_e32 v40, v32
	v_add_f32_e32 v32, 1.0, v34
	v_rcp_f32_e32 v41, v32
	v_mul_f32_e32 v32, v39, v72
	v_lshl_add_u64 v[36:37], v[54:55], 0, v[52:53]
	v_add_f32_e32 v34, v32, v32
	v_lshl_add_u64 v[36:37], v[36:37], 2, s[42:43]
	v_cmp_ngt_f32_e32 vcc, s9, v34
	s_waitcnt lgkmcnt(0)
	v_lshlrev_b32_e32 v38, 16, v38
	v_mul_f32_e32 v38, v41, v38
	v_mul_f32_e32 v38, v40, v38
	v_cvt_pk_bf16_f32 v33, v33, v38
	global_store_dword v[36:37], v33, off
	s_and_saveexec_b64 s[2:3], vcc
	s_xor_b64 s[2:3], exec, s[2:3]
	v_fmamk_f32 v33, v34, 0x3ab60b61, v169
	v_fmaak_f32 v33, v34, v33, 0x3d2aaaab
	v_fmaak_f32 v33, v34, v33, 0x3e2aaaab
	v_fma_f32 v33, v34, v33, 0.5
	v_fma_f32 v33, v34, v33, 1.0
	v_mul_f32_e64 v33, v33, -v34
	s_andn2_saveexec_b64 s[2:3], s[2:3]
	v_mul_f32_e32 v33, 0x3fb8aa3b, v34
	v_exp_f32_e32 v33, v33
	s_nop 0
	v_sub_f32_e32 v33, 1.0, v33
	s_or_b64 exec, exec, s[2:3]
	ds_read_u16 v36, v178 offset:2768
	v_add_f32_e32 v28, v28, v83
	v_add_f32_e32 v37, v35, v67
	v_mul_f32_e32 v28, 0xbfb8aa3b, v28
	v_mul_f32_e32 v37, 0xbfb8aa3b, v37
	v_exp_f32_e32 v28, v28
	v_exp_f32_e32 v37, v37
	v_max_f32_e32 v33, v33, v33
	v_max_f32_e32 v33, 0, v33
	v_add_f32_e32 v28, 1.0, v28
	v_rcp_f32_e32 v28, v28
	v_sqrt_f32_e32 v38, v33
	v_add_f32_e32 v33, 1.0, v37
	v_rcp_f32_e32 v37, v33
	v_mul_f32_e32 v28, v28, v84
	v_lshl_add_u64 v[34:35], v[42:43], 0, v[52:53]
	v_add_f32_e32 v33, v28, v28
	v_lshl_add_u64 v[34:35], v[34:35], 2, s[42:43]
	v_cmp_ngt_f32_e32 vcc, s9, v33
	s_waitcnt lgkmcnt(0)
	v_lshlrev_b32_e32 v36, 16, v36
	v_mul_f32_e32 v36, v37, v36
	v_mul_f32_e32 v36, v38, v36
	v_cvt_pk_bf16_f32 v32, v32, v36
	global_store_dword v[34:35], v32, off
	s_and_saveexec_b64 s[2:3], vcc
	s_xor_b64 s[2:3], exec, s[2:3]
	v_fmamk_f32 v32, v33, 0x3ab60b61, v169
	v_fmaak_f32 v32, v33, v32, 0x3d2aaaab
	v_fmaak_f32 v32, v33, v32, 0x3e2aaaab
	v_fma_f32 v32, v33, v32, 0.5
	v_fma_f32 v32, v33, v32, 1.0
	v_mul_f32_e64 v36, v32, -v33
	s_andn2_saveexec_b64 s[2:3], s[2:3]
	v_mul_f32_e32 v32, 0x3fb8aa3b, v33
	v_exp_f32_e32 v32, v32
	s_nop 0
	v_sub_f32_e32 v36, 1.0, v32
	s_or_b64 exec, exec, s[2:3]
	v_or_b32_e32 v32, 32, v66
	v_ashrrev_i32_e32 v33, 31, v32
	v_lshlrev_b64 v[32:33], 10, v[32:33]
	v_lshl_add_u64 v[38:39], v[32:33], 0, v[64:65]
	v_lshl_add_u64 v[34:35], v[38:39], 1, s[40:41]
	ds_read_u16 v37, v178 offset:4608
	v_add_f32_e32 v24, v24, v82
	v_mul_f32_e32 v24, 0xbfb8aa3b, v24
	v_exp_f32_e32 v24, v24
	v_max_f32_e32 v36, v36, v36
	v_max_f32_e32 v36, 0, v36
	v_sqrt_f32_e32 v36, v36
	v_add_f32_e32 v24, 1.0, v24
	v_rcp_f32_e32 v24, v24
	s_waitcnt lgkmcnt(0)
	v_lshlrev_b32_e32 v37, 16, v37
	v_mul_f32_e32 v24, v24, v37
	v_mul_f32_e32 v24, v36, v24
	v_cvt_pk_bf16_f32 v24, v28, v24
	v_lshl_add_u64 v[36:37], v[38:39], 2, s[42:43]
	global_store_dword v[36:37], v24, off
	v_add_f32_e32 v24, v29, v83
	v_mul_f32_e32 v24, 0xbfb8aa3b, v24
	v_exp_f32_e32 v24, v24
	s_nop 0
	v_add_f32_e32 v24, 1.0, v24
	v_rcp_f32_e32 v24, v24
	s_nop 0
	v_mul_f32_e32 v36, v24, v84
	v_add_f32_e32 v24, v36, v36
	v_cmp_ngt_f32_e32 vcc, s9, v24
	s_and_saveexec_b64 s[2:3], vcc
	s_xor_b64 s[2:3], exec, s[2:3]
	v_fmamk_f32 v28, v24, 0x3ab60b61, v169
	v_fmaak_f32 v28, v24, v28, 0x3d2aaaab
	v_fmaak_f32 v28, v24, v28, 0x3e2aaaab
	v_fma_f32 v28, v24, v28, 0.5
	v_fma_f32 v28, v24, v28, 1.0
	v_mul_f32_e64 v37, v28, -v24
	s_andn2_saveexec_b64 s[2:3], s[2:3]
	v_mul_f32_e32 v24, 0x3fb8aa3b, v24
	v_exp_f32_e32 v24, v24
	s_nop 0
	v_sub_f32_e32 v37, 1.0, v24
	s_or_b64 exec, exec, s[2:3]
	v_add_f32_e32 v24, v25, v82
	v_mul_f32_e32 v24, 0xbfb8aa3b, v24
	v_exp_f32_e32 v24, v24
	v_add_f32_e32 v30, v30, v83
	v_mul_f32_e32 v30, 0xbfb8aa3b, v30
	v_exp_f32_e32 v30, v30
	v_add_f32_e32 v24, 1.0, v24
	v_rcp_f32_e32 v40, v24
	v_or_b32_e32 v24, 33, v66
	v_ashrrev_i32_e32 v25, 31, v24
	v_lshlrev_b64 v[24:25], 10, v[24:25]
	v_lshl_add_u64 v[38:39], v[24:25], 0, v[64:65]
	v_lshl_add_u64 v[28:29], v[38:39], 1, s[40:41]
	ds_read_u16 v41, v178 offset:4752
	v_max_f32_e32 v37, v37, v37
	v_max_f32_e32 v37, 0, v37
	v_sqrt_f32_e32 v37, v37
	v_add_f32_e32 v30, 1.0, v30
	v_rcp_f32_e32 v30, v30
	s_waitcnt lgkmcnt(0)
;   __host__ __device__ __forceinline__ bf16_t* XC() const { return (bf16_t*)(wsl() + OFF_FFN); }
; __device__ __forceinline__ float bf2f(bf16_t h) { return __uint_as_float(((uint32_t)h) << 16); }
; __device__ __forceinline__ uint32_t pack2(float a, float b) { uint32_t r; asm("v_cvt_pk_bf16_f32 %0, %1, %2" : "=v"(r) : "v"(a), "v"(b)); return r; }
; __device__ __forceinline__ float sigmoidf_(float x) { return __builtin_amdgcn_rcpf(1.0f + __expf(-x)); }
; template <int EPI>
; __device__ __forceinline__ void gemm_tile(const Params& p, const EpiArgs& ea, const bf16_t* __restrict__ A, int lda,
;                                           const bf16_t* __restrict__ Bt, int K, int m0, int n0, char* smem) {
;     ...
;       for (int nh = 0; nh < 2; ++nh) {
;         int ch = (n0 >> 1) + wn * 32 + nh * 16 + fr;
;         float ba = p.lru_b_a[ea.dir * 1024 + ch], bx = p.lru_b_x[ea.dir * 1024 + ch];
;         float sp8 = -8.0f * log1pf(__expf(-p.lru_lam[ea.dir * 1024 + ch]));
; #pragma unroll
;         for (int j = 0; j < 4; ++j) {
;           float r = sigmoidf_(acc[mi][nh * 2][j] + ba);
;           float ig = sigmoidf_(acc[mi][nh * 2 + 1][j] + bx);
;           float la = r * sp8;
;           float x2 = 2.0f * la;
;           float poly = -x2 * (1.0f + x2 * (0.5f + x2 * (0.16666667f + x2 * (0.041666668f + x2 * (0.008333334f + x2 * 0.0013888889f)))));
;           float em = (x2 < -0.3f) ? (1.0f - __expf(x2)) : poly;
;           float u = bf2f(p.XC()[(size_t)(r0 + j) * D + ch]);
;           float inp = __builtin_amdgcn_sqrtf(fmaxf(em, 0.0f)) * (ig * u);
;           ea.outu[(size_t)(r0 + j) * D + ch] = pack2(la, inp);
;         }
	v_lshlrev_b32_e32 v41, 16, v41
	v_mul_f32_e32 v40, v40, v41
	v_mul_f32_e32 v37, v37, v40
	v_cvt_pk_bf16_f32 v40, v36, v37
	v_lshl_add_u64 v[36:37], v[38:39], 2, s[42:43]
	v_mul_f32_e32 v30, v30, v84
	global_store_dword v[36:37], v40, off
	v_add_f32_e32 v36, v30, v30
	v_cmp_ngt_f32_e32 vcc, s9, v36
	s_and_saveexec_b64 s[2:3], vcc
	s_xor_b64 s[2:3], exec, s[2:3]
	v_fmamk_f32 v37, v36, 0x3ab60b61, v169
	v_fmaak_f32 v37, v36, v37, 0x3d2aaaab
	v_fmaak_f32 v37, v36, v37, 0x3e2aaaab
	v_fma_f32 v37, v36, v37, 0.5
	v_fma_f32 v37, v36, v37, 1.0
	v_mul_f32_e64 v40, v37, -v36
	s_andn2_saveexec_b64 s[2:3], s[2:3]
	v_mul_f32_e32 v36, 0x3fb8aa3b, v36
	v_exp_f32_e32 v36, v36
	s_nop 0
	v_sub_f32_e32 v40, 1.0, v36
	s_or_b64 exec, exec, s[2:3]
	v_or_b32_e32 v36, 34, v66
	v_ashrrev_i32_e32 v37, 31, v36
	v_lshlrev_b64 v[36:37], 10, v[36:37]
	v_lshl_add_u64 v[42:43], v[36:37], 0, v[64:65]
	v_lshl_add_u64 v[38:39], v[42:43], 1, s[40:41]
	ds_read_u16 v41, v178 offset:4896
	v_add_f32_e32 v31, v31, v83
	v_mul_f32_e32 v31, 0xbfb8aa3b, v31
	v_add_f32_e32 v26, v26, v82
	v_exp_f32_e32 v31, v31
	v_mul_f32_e32 v26, 0xbfb8aa3b, v26
	v_exp_f32_e32 v26, v26
	v_max_f32_e32 v40, v40, v40
	v_add_f32_e32 v31, 1.0, v31
	v_rcp_f32_e32 v31, v31
	v_add_f32_e32 v26, 1.0, v26
	v_max_f32_e32 v40, 0, v40
	v_rcp_f32_e32 v45, v26
	v_sqrt_f32_e32 v44, v40
	v_mul_f32_e32 v40, v31, v84
	v_add_f32_e32 v26, v40, v40
	v_lshl_add_u64 v[42:43], v[42:43], 2, s[42:43]
	v_cmp_ngt_f32_e32 vcc, s9, v26
	s_waitcnt lgkmcnt(0)
	v_lshlrev_b32_e32 v31, 16, v41
	v_mul_f32_e32 v31, v45, v31
	v_mul_f32_e32 v31, v44, v31
	v_cvt_pk_bf16_f32 v30, v30, v31
	global_store_dword v[42:43], v30, off
	s_and_saveexec_b64 s[2:3], vcc
	s_xor_b64 s[2:3], exec, s[2:3]
	v_fmamk_f32 v30, v26, 0x3ab60b61, v169
	v_fmaak_f32 v30, v26, v30, 0x3d2aaaab
	v_fmaak_f32 v30, v26, v30, 0x3e2aaaab
	v_fma_f32 v30, v26, v30, 0.5
	v_fma_f32 v30, v26, v30, 1.0
	v_mul_f32_e64 v41, v30, -v26
	s_andn2_saveexec_b64 s[2:3], s[2:3]
	v_mul_f32_e32 v26, 0x3fb8aa3b, v26
	v_exp_f32_e32 v26, v26
	s_nop 0
	v_sub_f32_e32 v41, 1.0, v26
	s_or_b64 exec, exec, s[2:3]
	v_add_f32_e32 v26, v27, v82
	v_mul_f32_e32 v26, 0xbfb8aa3b, v26
	v_exp_f32_e32 v26, v26
	v_add_f32_e32 v20, v20, v74
	v_mul_f32_e32 v20, 0xbfb8aa3b, v20
	v_exp_f32_e32 v20, v20
	v_add_f32_e32 v26, 1.0, v26
	v_rcp_f32_e32 v44, v26
	v_or_b32_e32 v26, 35, v66
	v_ashrrev_i32_e32 v27, 31, v26
	v_lshlrev_b64 v[26:27], 10, v[26:27]
	v_lshl_add_u64 v[42:43], v[26:27], 0, v[64:65]
	v_lshl_add_u64 v[30:31], v[42:43], 1, s[40:41]
	ds_read_u16 v45, v178 offset:5040
	v_max_f32_e32 v41, v41, v41
	v_max_f32_e32 v41, 0, v41
	v_sqrt_f32_e32 v41, v41
	v_add_f32_e32 v20, 1.0, v20
	v_rcp_f32_e32 v20, v20
	s_waitcnt lgkmcnt(0)
	v_lshlrev_b32_e32 v45, 16, v45
	v_mul_f32_e32 v44, v44, v45
	v_mul_f32_e32 v41, v41, v44
	v_cvt_pk_bf16_f32 v44, v40, v41
	v_lshl_add_u64 v[40:41], v[42:43], 2, s[42:43]
	v_mul_f32_e32 v20, v20, v72
	global_store_dword v[40:41], v44, off
	v_add_f32_e32 v40, v20, v20
	v_cmp_ngt_f32_e32 vcc, s9, v40
	s_and_saveexec_b64 s[2:3], vcc
	s_xor_b64 s[2:3], exec, s[2:3]
	v_fmamk_f32 v41, v40, 0x3ab60b61, v169
	v_fmaak_f32 v41, v40, v41, 0x3d2aaaab
	v_fmaak_f32 v41, v40, v41, 0x3e2aaaab
	v_fma_f32 v41, v40, v41, 0.5
	v_fma_f32 v41, v40, v41, 1.0
	v_mul_f32_e64 v41, v41, -v40
	s_andn2_saveexec_b64 s[2:3], s[2:3]
	v_mul_f32_e32 v40, 0x3fb8aa3b, v40
	v_exp_f32_e32 v40, v40
	s_nop 0
	v_sub_f32_e32 v41, 1.0, v40
	s_or_b64 exec, exec, s[2:3]
	ds_read_u16 v34, v178 offset:4640
	v_add_f32_e32 v21, v21, v74
	v_add_f32_e32 v16, v16, v67
	v_mul_f32_e32 v21, 0xbfb8aa3b, v21
	v_mul_f32_e32 v16, 0xbfb8aa3b, v16
	v_exp_f32_e32 v21, v21
	v_exp_f32_e32 v16, v16
	v_max_f32_e32 v35, v41, v41
	v_max_f32_e32 v35, 0, v35
	v_add_f32_e32 v21, 1.0, v21
	v_rcp_f32_e32 v21, v21
	v_add_f32_e32 v16, 1.0, v16
	v_rcp_f32_e32 v40, v16
	v_sqrt_f32_e32 v35, v35
	v_mul_f32_e32 v16, v21, v72
	v_lshl_add_u64 v[32:33], v[32:33], 0, v[52:53]
	v_add_f32_e32 v21, v16, v16
	v_lshl_add_u64 v[32:33], v[32:33], 2, s[42:43]
	v_cmp_ngt_f32_e32 vcc, s9, v21
	s_waitcnt lgkmcnt(0)
	v_lshlrev_b32_e32 v34, 16, v34
	v_mul_f32_e32 v34, v40, v34
	v_mul_f32_e32 v34, v35, v34
	v_cvt_pk_bf16_f32 v20, v20, v34
	global_store_dword v[32:33], v20, off
	s_and_saveexec_b64 s[2:3], vcc
	s_xor_b64 s[2:3], exec, s[2:3]
	v_fmamk_f32 v20, v21, 0x3ab60b61, v169
	v_fmaak_f32 v20, v21, v20, 0x3d2aaaab
	v_fmaak_f32 v20, v21, v20, 0x3e2aaaab
	v_fma_f32 v20, v21, v20, 0.5
	v_fma_f32 v20, v21, v20, 1.0
	v_mul_f32_e64 v20, v20, -v21
	s_andn2_saveexec_b64 s[2:3], s[2:3]
	v_mul_f32_e32 v20, 0x3fb8aa3b, v21
	v_exp_f32_e32 v20, v20
	s_nop 0
	v_sub_f32_e32 v20, 1.0, v20
	s_or_b64 exec, exec, s[2:3]
	ds_read_u16 v21, v178 offset:4784
	v_add_f32_e32 v22, v22, v74
	v_add_f32_e32 v17, v17, v67
	v_mul_f32_e32 v22, 0xbfb8aa3b, v22
	v_mul_f32_e32 v17, 0xbfb8aa3b, v17
	v_exp_f32_e32 v22, v22
	v_exp_f32_e32 v17, v17
	v_max_f32_e32 v20, v20, v20
	v_max_f32_e32 v20, 0, v20
	v_add_f32_e32 v22, 1.0, v22
	v_rcp_f32_e32 v22, v22
	v_add_f32_e32 v17, 1.0, v17
	v_rcp_f32_e32 v29, v17
	v_sqrt_f32_e32 v28, v20
	v_mul_f32_e32 v17, v22, v72
	v_lshl_add_u64 v[24:25], v[24:25], 0, v[52:53]
	v_add_f32_e32 v20, v17, v17
	v_lshl_add_u64 v[24:25], v[24:25], 2, s[42:43]
	v_cmp_ngt_f32_e32 vcc, s9, v20
	s_waitcnt lgkmcnt(0)
;   __host__ __device__ __forceinline__ bf16_t* XC() const { return (bf16_t*)(wsl() + OFF_FFN); }
; __device__ __forceinline__ float bf2f(bf16_t h) { return __uint_as_float(((uint32_t)h) << 16); }
; __device__ __forceinline__ uint32_t pack2(float a, float b) { uint32_t r; asm("v_cvt_pk_bf16_f32 %0, %1, %2" : "=v"(r) : "v"(a), "v"(b)); return r; }
; __device__ __forceinline__ float sigmoidf_(float x) { return __builtin_amdgcn_rcpf(1.0f + __expf(-x)); }
; template <int EPI>
; __device__ __forceinline__ void gemm_tile(const Params& p, const EpiArgs& ea, const bf16_t* __restrict__ A, int lda,
;                                           const bf16_t* __restrict__ Bt, int K, int m0, int n0, char* smem) {
;     ...
;       for (int nh = 0; nh < 2; ++nh) {
;         int ch = (n0 >> 1) + wn * 32 + nh * 16 + fr;
;         float ba = p.lru_b_a[ea.dir * 1024 + ch], bx = p.lru_b_x[ea.dir * 1024 + ch];
;         float sp8 = -8.0f * log1pf(__expf(-p.lru_lam[ea.dir * 1024 + ch]));
; #pragma unroll
;         for (int j = 0; j < 4; ++j) {
;           float r = sigmoidf_(acc[mi][nh * 2][j] + ba);
;           float ig = sigmoidf_(acc[mi][nh * 2 + 1][j] + bx);
;           float la = r * sp8;
;           float x2 = 2.0f * la;
;           float poly = -x2 * (1.0f + x2 * (0.5f + x2 * (0.16666667f + x2 * (0.041666668f + x2 * (0.008333334f + x2 * 0.0013888889f)))));
;           float em = (x2 < -0.3f) ? (1.0f - __expf(x2)) : poly;
;           float u = bf2f(p.XC()[(size_t)(r0 + j) * D + ch]);
;           float inp = __builtin_amdgcn_sqrtf(fmaxf(em, 0.0f)) * (ig * u);
;           ea.outu[(size_t)(r0 + j) * D + ch] = pack2(la, inp);
;         }
	v_lshlrev_b32_e32 v21, 16, v21
	v_mul_f32_e32 v21, v29, v21
	v_mul_f32_e32 v21, v28, v21
	v_cvt_pk_bf16_f32 v16, v16, v21
	global_store_dword v[24:25], v16, off
	s_and_saveexec_b64 s[2:3], vcc
	s_xor_b64 s[2:3], exec, s[2:3]
	v_fmamk_f32 v16, v20, 0x3ab60b61, v169
	v_fmaak_f32 v16, v20, v16, 0x3d2aaaab
	v_fmaak_f32 v16, v20, v16, 0x3e2aaaab
	v_fma_f32 v16, v20, v16, 0.5
	v_fma_f32 v16, v20, v16, 1.0
	v_mul_f32_e64 v16, v16, -v20
	s_andn2_saveexec_b64 s[2:3], s[2:3]
	v_mul_f32_e32 v16, 0x3fb8aa3b, v20
	v_exp_f32_e32 v16, v16
	s_nop 0
	v_sub_f32_e32 v16, 1.0, v16
	s_or_b64 exec, exec, s[2:3]
	ds_read_u16 v22, v178 offset:4928
	v_add_f32_e32 v23, v23, v74
	v_add_f32_e32 v18, v18, v67
	v_mul_f32_e32 v23, 0xbfb8aa3b, v23
	v_mul_f32_e32 v18, 0xbfb8aa3b, v18
	v_exp_f32_e32 v23, v23
	v_exp_f32_e32 v18, v18
	v_max_f32_e32 v16, v16, v16
	v_max_f32_e32 v16, 0, v16
	v_add_f32_e32 v23, 1.0, v23
	v_rcp_f32_e32 v23, v23
	v_sqrt_f32_e32 v24, v16
	v_add_f32_e32 v16, 1.0, v18
	v_rcp_f32_e32 v25, v16
	v_mul_f32_e32 v16, v23, v72
	v_lshl_add_u64 v[20:21], v[36:37], 0, v[52:53]
	v_add_f32_e32 v18, v16, v16
	v_lshl_add_u64 v[20:21], v[20:21], 2, s[42:43]
	v_cmp_ngt_f32_e32 vcc, s9, v18
	s_waitcnt lgkmcnt(0)
	v_lshlrev_b32_e32 v22, 16, v22
	v_mul_f32_e32 v22, v25, v22
	v_mul_f32_e32 v22, v24, v22
	v_cvt_pk_bf16_f32 v17, v17, v22
	global_store_dword v[20:21], v17, off
	s_and_saveexec_b64 s[2:3], vcc
	s_xor_b64 s[2:3], exec, s[2:3]
	v_fmamk_f32 v17, v18, 0x3ab60b61, v169
	v_fmaak_f32 v17, v18, v17, 0x3d2aaaab
	v_fmaak_f32 v17, v18, v17, 0x3e2aaaab
	v_fma_f32 v17, v18, v17, 0.5
	v_fma_f32 v17, v18, v17, 1.0
	v_mul_f32_e64 v17, v17, -v18
	s_andn2_saveexec_b64 s[2:3], s[2:3]
	v_mul_f32_e32 v17, 0x3fb8aa3b, v18
	v_exp_f32_e32 v17, v17
	s_nop 0
	v_sub_f32_e32 v17, 1.0, v17
	s_or_b64 exec, exec, s[2:3]
	ds_read_u16 v20, v178 offset:5072
	v_add_f32_e32 v12, v12, v83
	v_add_f32_e32 v21, v19, v67
	v_mul_f32_e32 v12, 0xbfb8aa3b, v12
	v_mul_f32_e32 v21, 0xbfb8aa3b, v21
	v_exp_f32_e32 v12, v12
	v_exp_f32_e32 v21, v21
	v_max_f32_e32 v17, v17, v17
	v_max_f32_e32 v17, 0, v17
	v_add_f32_e32 v12, 1.0, v12
	v_rcp_f32_e32 v12, v12
	v_sqrt_f32_e32 v22, v17
	v_add_f32_e32 v17, 1.0, v21
	v_rcp_f32_e32 v21, v17
	v_mul_f32_e32 v12, v12, v84
	v_lshl_add_u64 v[18:19], v[26:27], 0, v[52:53]
	v_add_f32_e32 v17, v12, v12
	v_lshl_add_u64 v[18:19], v[18:19], 2, s[42:43]
	v_cmp_ngt_f32_e32 vcc, s9, v17
	s_waitcnt lgkmcnt(0)
	v_lshlrev_b32_e32 v20, 16, v20
	v_mul_f32_e32 v20, v21, v20
	v_mul_f32_e32 v20, v22, v20
	v_cvt_pk_bf16_f32 v16, v16, v20
	global_store_dword v[18:19], v16, off
	s_and_saveexec_b64 s[2:3], vcc
	s_xor_b64 s[2:3], exec, s[2:3]
	v_fmamk_f32 v16, v17, 0x3ab60b61, v169
	v_fmaak_f32 v16, v17, v16, 0x3d2aaaab
	v_fmaak_f32 v16, v17, v16, 0x3e2aaaab
	v_fma_f32 v16, v17, v16, 0.5
	v_fma_f32 v16, v17, v16, 1.0
	v_mul_f32_e64 v20, v16, -v17
	s_andn2_saveexec_b64 s[2:3], s[2:3]
	v_mul_f32_e32 v16, 0x3fb8aa3b, v17
	v_exp_f32_e32 v16, v16
	s_nop 0
	v_sub_f32_e32 v20, 1.0, v16
	s_or_b64 exec, exec, s[2:3]
	v_or_b32_e32 v16, 48, v66
	v_ashrrev_i32_e32 v17, 31, v16
	v_lshlrev_b64 v[16:17], 10, v[16:17]
	v_lshl_add_u64 v[22:23], v[16:17], 0, v[64:65]
	v_lshl_add_u64 v[18:19], v[22:23], 1, s[40:41]
	ds_read_u16 v21, v178 offset:6912
	v_add_f32_e32 v8, v8, v82
	v_mul_f32_e32 v8, 0xbfb8aa3b, v8
	v_exp_f32_e32 v8, v8
	v_max_f32_e32 v20, v20, v20
	v_max_f32_e32 v20, 0, v20
	v_sqrt_f32_e32 v20, v20
	v_add_f32_e32 v8, 1.0, v8
	v_rcp_f32_e32 v8, v8
	s_waitcnt lgkmcnt(0)
	v_lshlrev_b32_e32 v21, 16, v21
	v_mul_f32_e32 v8, v8, v21
	v_mul_f32_e32 v8, v20, v8
	v_cvt_pk_bf16_f32 v8, v12, v8
	v_lshl_add_u64 v[20:21], v[22:23], 2, s[42:43]
	global_store_dword v[20:21], v8, off
	v_add_f32_e32 v8, v13, v83
	v_mul_f32_e32 v8, 0xbfb8aa3b, v8
	v_exp_f32_e32 v8, v8
	s_nop 0
	v_add_f32_e32 v8, 1.0, v8
	v_rcp_f32_e32 v8, v8
	s_nop 0
	v_mul_f32_e32 v20, v8, v84
	v_add_f32_e32 v8, v20, v20
	v_cmp_ngt_f32_e32 vcc, s9, v8
	s_and_saveexec_b64 s[2:3], vcc
	s_xor_b64 s[2:3], exec, s[2:3]
	v_fmamk_f32 v12, v8, 0x3ab60b61, v169
	v_fmaak_f32 v12, v8, v12, 0x3d2aaaab
	v_fmaak_f32 v12, v8, v12, 0x3e2aaaab
	v_fma_f32 v12, v8, v12, 0.5
	v_fma_f32 v12, v8, v12, 1.0
	v_mul_f32_e64 v21, v12, -v8
	s_andn2_saveexec_b64 s[2:3], s[2:3]
	v_mul_f32_e32 v8, 0x3fb8aa3b, v8
	v_exp_f32_e32 v8, v8
	s_nop 0
	v_sub_f32_e32 v21, 1.0, v8
	s_or_b64 exec, exec, s[2:3]
	v_add_f32_e32 v8, v9, v82
	v_mul_f32_e32 v8, 0xbfb8aa3b, v8
	v_exp_f32_e32 v8, v8
	v_add_f32_e32 v14, v14, v83
	v_mul_f32_e32 v14, 0xbfb8aa3b, v14
	v_exp_f32_e32 v14, v14
	v_add_f32_e32 v8, 1.0, v8
	v_rcp_f32_e32 v24, v8
	v_or_b32_e32 v8, 49, v66
	v_ashrrev_i32_e32 v9, 31, v8
	v_lshlrev_b64 v[8:9], 10, v[8:9]
	v_lshl_add_u64 v[22:23], v[8:9], 0, v[64:65]
	v_lshl_add_u64 v[12:13], v[22:23], 1, s[40:41]
	ds_read_u16 v25, v178 offset:7056
	v_max_f32_e32 v21, v21, v21
	v_max_f32_e32 v21, 0, v21
	v_sqrt_f32_e32 v21, v21
	v_add_f32_e32 v14, 1.0, v14
	v_rcp_f32_e32 v14, v14
	s_waitcnt lgkmcnt(0)
;   __host__ __device__ __forceinline__ bf16_t* XC() const { return (bf16_t*)(wsl() + OFF_FFN); }
; __device__ __forceinline__ float bf2f(bf16_t h) { return __uint_as_float(((uint32_t)h) << 16); }
; __device__ __forceinline__ uint32_t pack2(float a, float b) { uint32_t r; asm("v_cvt_pk_bf16_f32 %0, %1, %2" : "=v"(r) : "v"(a), "v"(b)); return r; }
; __device__ __forceinline__ float sigmoidf_(float x) { return __builtin_amdgcn_rcpf(1.0f + __expf(-x)); }
; template <int EPI>
; __device__ __forceinline__ void gemm_tile(const Params& p, const EpiArgs& ea, const bf16_t* __restrict__ A, int lda,
;                                           const bf16_t* __restrict__ Bt, int K, int m0, int n0, char* smem) {
;     ...
;       for (int nh = 0; nh < 2; ++nh) {
;         int ch = (n0 >> 1) + wn * 32 + nh * 16 + fr;
;         float ba = p.lru_b_a[ea.dir * 1024 + ch], bx = p.lru_b_x[ea.dir * 1024 + ch];
;         float sp8 = -8.0f * log1pf(__expf(-p.lru_lam[ea.dir * 1024 + ch]));
; #pragma unroll
;         for (int j = 0; j < 4; ++j) {
;           float r = sigmoidf_(acc[mi][nh * 2][j] + ba);
;           float ig = sigmoidf_(acc[mi][nh * 2 + 1][j] + bx);
;           float la = r * sp8;
;           float x2 = 2.0f * la;
;           float poly = -x2 * (1.0f + x2 * (0.5f + x2 * (0.16666667f + x2 * (0.041666668f + x2 * (0.008333334f + x2 * 0.0013888889f)))));
;           float em = (x2 < -0.3f) ? (1.0f - __expf(x2)) : poly;
;           float u = bf2f(p.XC()[(size_t)(r0 + j) * D + ch]);
;           float inp = __builtin_amdgcn_sqrtf(fmaxf(em, 0.0f)) * (ig * u);
;           ea.outu[(size_t)(r0 + j) * D + ch] = pack2(la, inp);
;         }
	v_lshlrev_b32_e32 v25, 16, v25
	v_mul_f32_e32 v24, v24, v25
	v_mul_f32_e32 v21, v21, v24
	v_cvt_pk_bf16_f32 v24, v20, v21
	v_lshl_add_u64 v[20:21], v[22:23], 2, s[42:43]
	v_mul_f32_e32 v14, v14, v84
	global_store_dword v[20:21], v24, off
	v_add_f32_e32 v20, v14, v14
	v_cmp_ngt_f32_e32 vcc, s9, v20
	s_and_saveexec_b64 s[2:3], vcc
	s_xor_b64 s[2:3], exec, s[2:3]
	v_fmamk_f32 v21, v20, 0x3ab60b61, v169
	v_fmaak_f32 v21, v20, v21, 0x3d2aaaab
	v_fmaak_f32 v21, v20, v21, 0x3e2aaaab
	v_fma_f32 v21, v20, v21, 0.5
	v_fma_f32 v21, v20, v21, 1.0
	v_mul_f32_e64 v24, v21, -v20
	s_andn2_saveexec_b64 s[2:3], s[2:3]
	v_mul_f32_e32 v20, 0x3fb8aa3b, v20
	v_exp_f32_e32 v20, v20
	s_nop 0
	v_sub_f32_e32 v24, 1.0, v20
	s_or_b64 exec, exec, s[2:3]
	v_or_b32_e32 v20, 50, v66
	v_ashrrev_i32_e32 v21, 31, v20
	v_lshlrev_b64 v[20:21], 10, v[20:21]
	v_lshl_add_u64 v[26:27], v[20:21], 0, v[64:65]
	v_lshl_add_u64 v[22:23], v[26:27], 1, s[40:41]
	ds_read_u16 v25, v178 offset:7200
	v_add_f32_e32 v15, v15, v83
	v_mul_f32_e32 v15, 0xbfb8aa3b, v15
	v_add_f32_e32 v10, v10, v82
	v_exp_f32_e32 v15, v15
	v_mul_f32_e32 v10, 0xbfb8aa3b, v10
	v_exp_f32_e32 v10, v10
	v_max_f32_e32 v24, v24, v24
	v_add_f32_e32 v15, 1.0, v15
	v_rcp_f32_e32 v15, v15
	v_add_f32_e32 v10, 1.0, v10
	v_max_f32_e32 v24, 0, v24
	v_rcp_f32_e32 v29, v10
	v_sqrt_f32_e32 v28, v24
	v_mul_f32_e32 v24, v15, v84
	v_add_f32_e32 v10, v24, v24
	v_lshl_add_u64 v[26:27], v[26:27], 2, s[42:43]
	v_cmp_ngt_f32_e32 vcc, s9, v10
	s_waitcnt lgkmcnt(0)
	v_lshlrev_b32_e32 v15, 16, v25
	v_mul_f32_e32 v15, v29, v15
	v_mul_f32_e32 v15, v28, v15
	v_cvt_pk_bf16_f32 v14, v14, v15
	global_store_dword v[26:27], v14, off
	s_and_saveexec_b64 s[2:3], vcc
	s_xor_b64 s[2:3], exec, s[2:3]
	v_fmamk_f32 v14, v10, 0x3ab60b61, v169
	v_fmaak_f32 v14, v10, v14, 0x3d2aaaab
	v_fmaak_f32 v14, v10, v14, 0x3e2aaaab
	v_fma_f32 v14, v10, v14, 0.5
	v_fma_f32 v14, v10, v14, 1.0
	v_mul_f32_e64 v25, v14, -v10
	s_andn2_saveexec_b64 s[2:3], s[2:3]
	v_mul_f32_e32 v10, 0x3fb8aa3b, v10
	v_exp_f32_e32 v10, v10
	s_nop 0
	v_sub_f32_e32 v25, 1.0, v10
	s_or_b64 exec, exec, s[2:3]
	v_add_f32_e32 v10, v11, v82
	v_mul_f32_e32 v10, 0xbfb8aa3b, v10
	v_exp_f32_e32 v10, v10
	v_add_f32_e32 v4, v4, v74
	v_mul_f32_e32 v4, 0xbfb8aa3b, v4
	v_exp_f32_e32 v4, v4
	v_add_f32_e32 v10, 1.0, v10
	v_rcp_f32_e32 v28, v10
	v_or_b32_e32 v10, 51, v66
	v_ashrrev_i32_e32 v11, 31, v10
	v_lshlrev_b64 v[10:11], 10, v[10:11]
	v_lshl_add_u64 v[26:27], v[10:11], 0, v[64:65]
	v_lshl_add_u64 v[14:15], v[26:27], 1, s[40:41]
	ds_read_u16 v29, v178 offset:7344
	v_max_f32_e32 v25, v25, v25
	v_max_f32_e32 v25, 0, v25
	v_sqrt_f32_e32 v25, v25
	v_add_f32_e32 v4, 1.0, v4
	v_rcp_f32_e32 v4, v4
	s_waitcnt lgkmcnt(0)
	v_lshlrev_b32_e32 v29, 16, v29
	v_mul_f32_e32 v28, v28, v29
	v_mul_f32_e32 v25, v25, v28
	v_cvt_pk_bf16_f32 v28, v24, v25
	v_lshl_add_u64 v[24:25], v[26:27], 2, s[42:43]
	v_mul_f32_e32 v4, v4, v72
	global_store_dword v[24:25], v28, off
	v_add_f32_e32 v24, v4, v4
	v_cmp_ngt_f32_e32 vcc, s9, v24
	s_and_saveexec_b64 s[2:3], vcc
	s_xor_b64 s[2:3], exec, s[2:3]
	v_fmamk_f32 v25, v24, 0x3ab60b61, v169
	v_fmaak_f32 v25, v24, v25, 0x3d2aaaab
	v_fmaak_f32 v25, v24, v25, 0x3e2aaaab
	v_fma_f32 v25, v24, v25, 0.5
	v_fma_f32 v25, v24, v25, 1.0
	v_mul_f32_e64 v25, v25, -v24
	s_andn2_saveexec_b64 s[2:3], s[2:3]
	v_mul_f32_e32 v24, 0x3fb8aa3b, v24
	v_exp_f32_e32 v24, v24
	s_nop 0
	v_sub_f32_e32 v25, 1.0, v24
	s_or_b64 exec, exec, s[2:3]
	ds_read_u16 v18, v178 offset:6944
	v_add_f32_e32 v5, v5, v74
	v_add_f32_e32 v0, v0, v67
	v_mul_f32_e32 v5, 0xbfb8aa3b, v5
	v_mul_f32_e32 v0, 0xbfb8aa3b, v0
	v_exp_f32_e32 v5, v5
	v_exp_f32_e32 v0, v0
	v_max_f32_e32 v19, v25, v25
	v_max_f32_e32 v19, 0, v19
	v_add_f32_e32 v5, 1.0, v5
	v_rcp_f32_e32 v5, v5
	v_add_f32_e32 v0, 1.0, v0
	v_rcp_f32_e32 v24, v0
	v_sqrt_f32_e32 v19, v19
	v_mul_f32_e32 v0, v5, v72
	v_lshl_add_u64 v[16:17], v[16:17], 0, v[52:53]
	v_add_f32_e32 v5, v0, v0
	v_lshl_add_u64 v[16:17], v[16:17], 2, s[42:43]
	v_cmp_ngt_f32_e32 vcc, s9, v5
	s_waitcnt lgkmcnt(0)
;   __host__ __device__ __forceinline__ bf16_t* XC() const { return (bf16_t*)(wsl() + OFF_FFN); }
; __device__ __forceinline__ float bf2f(bf16_t h) { return __uint_as_float(((uint32_t)h) << 16); }
; __device__ __forceinline__ uint32_t pack2(float a, float b) { uint32_t r; asm("v_cvt_pk_bf16_f32 %0, %1, %2" : "=v"(r) : "v"(a), "v"(b)); return r; }
; __device__ __forceinline__ float sigmoidf_(float x) { return __builtin_amdgcn_rcpf(1.0f + __expf(-x)); }
; template <int EPI>
; __device__ __forceinline__ void gemm_tile(const Params& p, const EpiArgs& ea, const bf16_t* __restrict__ A, int lda,
;                                           const bf16_t* __restrict__ Bt, int K, int m0, int n0, char* smem) {
;     ...
;       for (int nh = 0; nh < 2; ++nh) {
;         int ch = (n0 >> 1) + wn * 32 + nh * 16 + fr;
;         float ba = p.lru_b_a[ea.dir * 1024 + ch], bx = p.lru_b_x[ea.dir * 1024 + ch];
;         float sp8 = -8.0f * log1pf(__expf(-p.lru_lam[ea.dir * 1024 + ch]));
; #pragma unroll
;         for (int j = 0; j < 4; ++j) {
;           float r = sigmoidf_(acc[mi][nh * 2][j] + ba);
;           float ig = sigmoidf_(acc[mi][nh * 2 + 1][j] + bx);
;           float la = r * sp8;
;           float x2 = 2.0f * la;
;           float poly = -x2 * (1.0f + x2 * (0.5f + x2 * (0.16666667f + x2 * (0.041666668f + x2 * (0.008333334f + x2 * 0.0013888889f)))));
;           float em = (x2 < -0.3f) ? (1.0f - __expf(x2)) : poly;
;           float u = bf2f(p.XC()[(size_t)(r0 + j) * D + ch]);
;           float inp = __builtin_amdgcn_sqrtf(fmaxf(em, 0.0f)) * (ig * u);
;           ea.outu[(size_t)(r0 + j) * D + ch] = pack2(la, inp);
;         }
	v_lshlrev_b32_e32 v18, 16, v18
	v_mul_f32_e32 v18, v24, v18
	v_mul_f32_e32 v18, v19, v18
	v_cvt_pk_bf16_f32 v4, v4, v18
	global_store_dword v[16:17], v4, off
	s_and_saveexec_b64 s[2:3], vcc
	s_xor_b64 s[2:3], exec, s[2:3]
	v_fmamk_f32 v4, v5, 0x3ab60b61, v169
	v_fmaak_f32 v4, v5, v4, 0x3d2aaaab
	v_fmaak_f32 v4, v5, v4, 0x3e2aaaab
	v_fma_f32 v4, v5, v4, 0.5
	v_fma_f32 v4, v5, v4, 1.0
	v_mul_f32_e64 v4, v4, -v5
	s_andn2_saveexec_b64 s[2:3], s[2:3]
	v_mul_f32_e32 v4, 0x3fb8aa3b, v5
	v_exp_f32_e32 v4, v4
	s_nop 0
	v_sub_f32_e32 v4, 1.0, v4
	s_or_b64 exec, exec, s[2:3]
	ds_read_u16 v5, v178 offset:7088
	v_add_f32_e32 v6, v6, v74
	v_add_f32_e32 v1, v1, v67
	v_mul_f32_e32 v6, 0xbfb8aa3b, v6
	v_mul_f32_e32 v1, 0xbfb8aa3b, v1
	v_exp_f32_e32 v6, v6
	v_exp_f32_e32 v1, v1
	v_max_f32_e32 v4, v4, v4
	v_max_f32_e32 v4, 0, v4
	v_add_f32_e32 v6, 1.0, v6
	v_rcp_f32_e32 v6, v6
	v_add_f32_e32 v1, 1.0, v1
	v_rcp_f32_e32 v13, v1
	v_sqrt_f32_e32 v12, v4
	v_mul_f32_e32 v1, v6, v72
	v_lshl_add_u64 v[8:9], v[8:9], 0, v[52:53]
	v_add_f32_e32 v4, v1, v1
	v_lshl_add_u64 v[8:9], v[8:9], 2, s[42:43]
	v_cmp_ngt_f32_e32 vcc, s9, v4
	s_waitcnt lgkmcnt(0)
	v_lshlrev_b32_e32 v5, 16, v5
	v_mul_f32_e32 v5, v13, v5
	v_mul_f32_e32 v5, v12, v5
	v_cvt_pk_bf16_f32 v0, v0, v5
	global_store_dword v[8:9], v0, off
	s_and_saveexec_b64 s[2:3], vcc
	s_xor_b64 s[2:3], exec, s[2:3]
	v_fmamk_f32 v0, v4, 0x3ab60b61, v169
	v_fmaak_f32 v0, v4, v0, 0x3d2aaaab
	v_fmaak_f32 v0, v4, v0, 0x3e2aaaab
	v_fma_f32 v0, v4, v0, 0.5
	v_fma_f32 v0, v4, v0, 1.0
	v_mul_f32_e64 v0, v0, -v4
	s_andn2_saveexec_b64 s[2:3], s[2:3]
	v_mul_f32_e32 v0, 0x3fb8aa3b, v4
	v_exp_f32_e32 v0, v0
	s_nop 0
	v_sub_f32_e32 v0, 1.0, v0
	s_or_b64 exec, exec, s[2:3]
	ds_read_u16 v6, v178 offset:7232
	v_add_f32_e32 v7, v7, v74
	v_add_f32_e32 v2, v2, v67
	v_mul_f32_e32 v7, 0xbfb8aa3b, v7
	v_mul_f32_e32 v2, 0xbfb8aa3b, v2
	v_exp_f32_e32 v7, v7
	v_exp_f32_e32 v2, v2
	v_max_f32_e32 v0, v0, v0
	v_max_f32_e32 v0, 0, v0
	v_add_f32_e32 v7, 1.0, v7
	v_rcp_f32_e32 v7, v7
	v_sqrt_f32_e32 v8, v0
	v_add_f32_e32 v0, 1.0, v2
	v_rcp_f32_e32 v9, v0
	v_mul_f32_e32 v0, v7, v72
	v_lshl_add_u64 v[4:5], v[20:21], 0, v[52:53]
	v_add_f32_e32 v2, v0, v0
	v_lshl_add_u64 v[4:5], v[4:5], 2, s[42:43]
	v_cmp_ngt_f32_e32 vcc, s9, v2
	s_waitcnt lgkmcnt(0)
	v_lshlrev_b32_e32 v6, 16, v6
	v_mul_f32_e32 v6, v9, v6
	v_mul_f32_e32 v6, v8, v6
	v_cvt_pk_bf16_f32 v1, v1, v6
	global_store_dword v[4:5], v1, off
	s_and_saveexec_b64 s[2:3], vcc
	s_xor_b64 s[2:3], exec, s[2:3]
	v_fmamk_f32 v1, v2, 0x3ab60b61, v169
	v_fmaak_f32 v1, v2, v1, 0x3d2aaaab
	v_fmaak_f32 v1, v2, v1, 0x3e2aaaab
	v_fma_f32 v1, v2, v1, 0.5
	v_fma_f32 v1, v2, v1, 1.0
	v_mul_f32_e64 v1, v1, -v2
	s_andn2_saveexec_b64 s[2:3], s[2:3]
	v_mul_f32_e32 v1, 0x3fb8aa3b, v2
	v_exp_f32_e32 v1, v1
	s_nop 0
	v_sub_f32_e32 v1, 1.0, v1
	s_or_b64 exec, exec, s[2:3]
	ds_read_u16 v4, v178 offset:7376
	v_add_f32_e32 v2, v3, v67
	v_mul_f32_e32 v2, 0xbfb8aa3b, v2
	v_exp_f32_e32 v5, v2
	v_max_f32_e32 v1, v1, v1
	v_max_f32_e32 v1, 0, v1
	v_sqrt_f32_e32 v1, v1
	v_add_f32_e32 v5, 1.0, v5
	v_rcp_f32_e32 v5, v5
	v_lshl_add_u64 v[2:3], v[10:11], 0, v[52:53]
	v_lshl_add_u64 v[2:3], v[2:3], 2, s[42:43]
	s_waitcnt lgkmcnt(0)
	v_lshlrev_b32_e32 v4, 16, v4
	v_mul_f32_e32 v4, v5, v4
	v_mul_f32_e32 v1, v1, v4
	v_cvt_pk_bf16_f32 v0, v0, v1
	global_store_dword v[2:3], v0, off
	s_barrier
	s_mov_b32 s9, 0
